# combo3 plus: scan next-chunk V/P LDS-DMA issued after the q/k register loads with counted vmcnt (no forced DMA drain at pass 2); M3 filler weight-conversion loops issue all 16 loads before consuming (
# speedup vs baseline: 1.0017x; 1.0017x over previous
; #define LAS __attribute__((address_space(3)))
; __device__ __forceinline__ s16x4 tr_read(LAS unsigned char* p) { return __builtin_bit_cast(s16x4, __builtin_amdgcn_ds_read_tr16_b64_v4i16((LAS v4i16_t*)p)); }
; __device__ __forceinline__ bf16x8 pack8(s16x4 lo, s16x4 hi) { return (bf16x8){lo[0], lo[1], lo[2], lo[3], hi[0], hi[1], hi[2], hi[3]}; }
; template <int M, int N, class Fn> __device__ __forceinline__ void mattn_sfor(Fn&& f) { if constexpr (M < N) { f(std::integral_constant<int, M>{}); mattn_sfor<M + 1, N>(f); } }
; __device__ __forceinline__ void scan_phase(const Frame& F, const bf16_t* Q, const bf16_t* K, const bf16_t* V, const bf16_t* PB, bf16_t* OF, bf16_t* OB, int half) {
;     ...
;             for (int p = 0; p < 4; ++p) {
;                 if (p < 3 || more) SCAN_WRITE_QK((p + 1) & 1);
;                 if (p == 1 && more) SCAN_DMA_VP(cn);
;                 if (p < 2) SCAN_LOAD_QK(c, p + 2); else if (more) SCAN_LOAD_QK(cn, p - 2);
;                 if (p == 0) {
; #pragma unroll
;                     for (int ks = 0; ks < 4; ++ks) { const s16x4 lo = tr_read(bVlo + 32 * ks * 256), hi = tr_read(bVhi + 32 * ks * 256); Vf[ks] = pack8(lo, hi); }
;                     __builtin_amdgcn_sched_barrier(0);
;                     { u32x4 pwb[2];
;                       { constexpr int q0_ = pv_pair(dir, 0); pwb[0] = *(const LAS u32x4*)(bPk[q0_ & 3] + 16 * (q0_ >> 2) * 256); }
;                       __builtin_amdgcn_sched_group_barrier(0x100, 1, 0);
;                       mattn_sfor<0, 20>([&](auto n_) { constexpr int n = decltype(n_)::value, pr = pv_pair(dir, n), it = pr >> 2, ks = pr & 3, dks = ks - (it >> 1);
;                           if constexpr (n + 1 < 20) { constexpr int nx = pv_pair(dir, n + 1); pwb[(n + 1) & 1] = *(const LAS u32x4*)(bPk[nx & 3] + 16 * (nx >> 2) * 256); }
;                           u32x4 pw = pwb[n & 1];
;                           if constexpr (dks == 0) { pw.x &= pmk[it & 1][0]; pw.y &= pmk[it & 1][1]; pw.z &= pmk[it & 1][2]; pw.w &= pmk[it & 1][3]; }
;                           Ot[it] = __builtin_amdgcn_mfma_f32_16x16x32_bf16(Vf[ks], __builtin_bit_cast(bf16x8, pw), Ot[it], 0, 0, 0);
;                           __builtin_amdgcn_sched_group_barrier(0x100, 1, 0); __builtin_amdgcn_sched_group_barrier(0x8, 1, 0); }); }
.LBB0_978:
	v_lshl_add_u64 v[158:159], v[154:155], 0, s[42:43]
	s_mov_b32 s12, 0x10780000
	v_add_co_u32_e32 v72, vcc, s12, v158
	v_mov_b32_e32 v192, v161
	v_mov_b32_e32 v74, v162
	v_lshl_add_u64 v[156:157], v[152:153], 0, s[42:43]
	v_addc_co_u32_e32 v73, vcc, 0, v159, vcc
	s_mov_b32 s12, 0x4a880000
	global_load_dwordx4 v[96:99], v[72:73], off offset:256
	v_add_co_u32_e32 v72, vcc, s12, v156
	s_mov_b32 s12, 0x107c0000
	s_nop 0
	v_addc_co_u32_e32 v73, vcc, 0, v157, vcc
	global_load_dwordx4 v[100:103], v[72:73], off offset:256
	v_add_co_u32_e32 v72, vcc, s12, v158
	s_mov_b32 s12, 0x4a8c0000
	s_nop 0
	v_addc_co_u32_e32 v73, vcc, 0, v159, vcc
	global_load_dwordx4 v[104:107], v[72:73], off offset:256
	v_add_co_u32_e32 v72, vcc, s12, v156
	s_waitcnt vmcnt(14)
	ds_write_b128 v214, v[64:67] offset:16384
	v_addc_co_u32_e32 v73, vcc, 0, v157, vcc
	global_load_dwordx4 v[108:111], v[72:73], off offset:256
	s_waitcnt vmcnt(14)
	ds_write_b128 v214, v[68:71] offset:49152
	s_waitcnt vmcnt(13)
	ds_write_b128 v214, v[76:79] offset:24576
	s_waitcnt vmcnt(12)
	ds_write_b128 v214, v[84:87] offset:57344
	v_add_u32_e32 v64, v175, v168
	v_add_u32_e32 v65, v169, v168
	v_lshlrev_b32_e32 v112, 3, v74
	ds_read_b64_tr_b16 v[72:73], v64
	ds_read_b64_tr_b16 v[80:81], v64 offset:8192
	ds_read_b64_tr_b16 v[88:89], v64 offset:16384
	ds_read_b64_tr_b16 v[92:93], v64 offset:24576
	ds_read_b64_tr_b16 v[74:75], v65 offset:1024
	ds_read_b64_tr_b16 v[82:83], v65 offset:9216
	ds_read_b64_tr_b16 v[90:91], v65 offset:17408
	ds_read_b64_tr_b16 v[94:95], v65 offset:25600
	v_cvt_f32_i32_e32 v124, v112
	s_cmp_lt_u32 s59, s73
	s_cselect_b64 s[44:45], -1, 0
	s_cmp_ge_u32 s59, s73
	v_add_u32_e32 v84, v170, v171
	ds_read_b128 v[64:67], v84
	v_add_u32_e32 v116, v170, v172
	ds_read_b128 v[68:71], v116
	v_add_u32_e32 v120, v170, v173
	v_add_u32_e32 v125, v170, v174
	s_waitcnt lgkmcnt(1)
	v_and_b32_e32 v64, v64, v191
	v_and_b32_e32 v65, v65, v198
	v_and_b32_e32 v66, v66, v199
	v_and_b32_e32 v67, v67, v200
	s_nop 1
	v_mfma_f32_16x16x32_bf16 v[64:67], v[72:75], v[64:67], 0
	ds_read_b128 v[76:79], v120
	s_waitcnt lgkmcnt(1)
	v_mfma_f32_16x16x32_bf16 v[64:67], v[80:83], v[68:71], v[64:67]
	ds_read_b128 v[68:71], v125
	s_waitcnt lgkmcnt(1)
	v_mfma_f32_16x16x32_bf16 v[64:67], v[88:91], v[76:79], v[64:67]
	ds_read_b128 v[76:79], v84 offset:4096
	s_waitcnt lgkmcnt(0)
	v_and_b32_e32 v76, v76, v201
	v_mfma_f32_16x16x32_bf16 v[64:67], v[92:95], v[68:71], v[64:67]
	ds_read_b128 v[68:71], v116 offset:4096
	v_and_b32_e32 v77, v77, v202
	v_and_b32_e32 v78, v78, v203
	v_and_b32_e32 v79, v79, v204
	s_nop 1
	v_mfma_f32_16x16x32_bf16 v[76:79], v[72:75], v[76:79], 0
	ds_read_b128 v[84:87], v120 offset:4096
	s_waitcnt lgkmcnt(1)
	v_mfma_f32_16x16x32_bf16 v[68:71], v[80:83], v[68:71], v[76:79]
	s_nop 4
	ds_read_b128 v[76:79], v125 offset:4096
	s_waitcnt lgkmcnt(1)
	v_mfma_f32_16x16x32_bf16 v[68:71], v[88:91], v[84:87], v[68:71]
	ds_read_b128 v[84:87], v116 offset:8192
	s_waitcnt lgkmcnt(0)
	v_and_b32_e32 v84, v84, v191
	v_mfma_f32_16x16x32_bf16 v[68:71], v[92:95], v[76:79], v[68:71]
	ds_read_b128 v[76:79], v120 offset:8192
	v_and_b32_e32 v85, v85, v198
	v_and_b32_e32 v86, v86, v199
	v_and_b32_e32 v87, v87, v200
	s_nop 1
	v_mfma_f32_16x16x32_bf16 v[84:87], v[80:83], v[84:87], 0
	ds_read_b128 v[112:115], v125 offset:8192
	s_waitcnt lgkmcnt(1)
	v_mfma_f32_16x16x32_bf16 v[76:79], v[88:91], v[76:79], v[84:87]
	s_nop 4
	ds_read_b128 v[84:87], v116 offset:12288
	s_waitcnt lgkmcnt(1)
	v_mfma_f32_16x16x32_bf16 v[76:79], v[92:95], v[112:115], v[76:79]
	ds_read_b128 v[112:115], v120 offset:12288
	s_waitcnt lgkmcnt(1)
	v_and_b32_e32 v84, v84, v201
	v_and_b32_e32 v85, v85, v202
	v_and_b32_e32 v86, v86, v203
	v_and_b32_e32 v87, v87, v204
	s_nop 1
	v_mfma_f32_16x16x32_bf16 v[84:87], v[80:83], v[84:87], 0
	ds_read_b128 v[116:119], v125 offset:12288
	s_waitcnt lgkmcnt(1)
	v_mfma_f32_16x16x32_bf16 v[84:87], v[88:91], v[112:115], v[84:87]
	ds_read_b128 v[112:115], v120 offset:16384
	s_waitcnt lgkmcnt(0)
	v_and_b32_e32 v112, v112, v191
	v_and_b32_e32 v113, v113, v198
	v_and_b32_e32 v114, v114, v199
	v_and_b32_e32 v115, v115, v200
	v_mfma_f32_16x16x32_bf16 v[84:87], v[92:95], v[116:119], v[84:87]
	ds_read_b128 v[116:119], v125 offset:16384
	v_mfma_f32_16x16x32_bf16 v[112:115], v[88:91], v[112:115], 0
	ds_read_b128 v[120:123], v120 offset:20480
	s_waitcnt lgkmcnt(1)
	v_mfma_f32_16x16x32_bf16 v[128:131], v[92:95], v[116:119], v[112:115]
	s_waitcnt lgkmcnt(0)
	v_and_b32_e32 v116, v120, v201
	v_and_b32_e32 v117, v121, v202
	s_nop 1
	ds_read_b128 v[112:115], v125 offset:20480
	v_and_b32_e32 v118, v122, v203
	v_and_b32_e32 v119, v123, v204
	s_nop 1
	v_mfma_f32_16x16x32_bf16 v[116:119], v[88:91], v[116:119], 0
	ds_read_b128 v[120:123], v125 offset:24576
	s_waitcnt lgkmcnt(1)
	v_mfma_f32_16x16x32_bf16 v[132:135], v[92:95], v[112:115], v[116:119]
	ds_read_b128 v[112:115], v125 offset:28672
	s_waitcnt lgkmcnt(0)
; __device__ __forceinline__ unsigned cvt_pk_bf16(float lo, float hi) { unsigned r; asm volatile("v_cvt_pk_bf16_f32 %0, %1, %2" : "=v"(r) : "v"(lo), "v"(hi)); return r; }
; __device__ __forceinline__ float bf_lo(unsigned w) { return __uint_as_float(w << 16); }
; __device__ __forceinline__ float bf_hi(unsigned w) { return __uint_as_float(w & 0xffff0000u); }
; #define SCAN_QREAD(b_, it_) do { _Pragma("unroll") for (int ks = 0; ks < 2; ++ks) { const int qo = ((p & 1) ? LQ1 : LQ0) + 16 * (it_) * QS; \
;                         const u32x2 lo = *(const volatile LAS u32x2*)(bQs[ks][0] + qo), hi = *(const volatile LAS u32x2*)(bQs[ks][1] + qo);     qf[b_][ks] = (u32x4){lo.x, lo.y, hi.x, hi.y}; } } while (0)
; __device__ __forceinline__ void scan_phase(const Frame& F, const bf16_t* Q, const bf16_t* K, const bf16_t* V, const bf16_t* PB, bf16_t* OF, bf16_t* OB, int half) {
;     ...
;                     { float fk = __builtin_amdgcn_exp2f(lg2 * (float)(dir ? 8 * quad_l : 127 - 8 * quad_l));
; #pragma unroll
;                       for (int ks = 0; ks < 4; ++ks) { u32x4 vw = __builtin_bit_cast(u32x4, Vf[ks]); float f = fk;
; #pragma unroll
;                         for (int e2 = 0; e2 < 4; ++e2) { const float f0 = f, f1 = f * gm1; f = f1 * gm1;
;                             vw[e2] = cvt_pk_bf16(bf_lo(vw[e2]) * f0, bf_hi(vw[e2]) * f1); }
;                         Vf[ks] = __builtin_bit_cast(bf16x8, vw); fk *= gm32; } }
;                 }
;                 __builtin_amdgcn_sched_barrier(0);
;                 {
;                     bf16x8 Rf[2];
; #pragma unroll
;                     for (int ks = 0; ks < 2; ++ks) { const f32x4 r0v = Rt[4 * p + 2 * ks], r1v = Rt[4 * p + 2 * ks + 1];
;                         const u32x4 wvv = {cvt_pk_bf16(r0v[0], r0v[1]), cvt_pk_bf16(r0v[2], r0v[3]), cvt_pk_bf16(r1v[0], r1v[1]), cvt_pk_bf16(r1v[2], r1v[3])};
;                         Rf[ks] = __builtin_bit_cast(bf16x8, wvv); }
;                     u32x4 qf[2][2];
;     ...
;                     SCAN_QREAD(0, 0);
; #pragma unroll
;                     for (int it = 0; it < 8; ++it) { if (it < 7) SCAN_QREAD((it + 1) & 1, it + 1);
; #pragma unroll
;                         for (int ks = 0; ks < 2; ++ks) Ot[it] = __builtin_amdgcn_mfma_f32_16x16x32_bf16(Rf[ks], __builtin_bit_cast(bf16x8, qf[it & 1][ks]), Ot[it], 0, 0, 0); }
	v_and_b32_e32 v112, v112, v201
	s_nop 1
	v_and_b32_e32 v116, v120, v191
	v_and_b32_e32 v117, v121, v198
	v_and_b32_e32 v118, v122, v199
	v_and_b32_e32 v119, v123, v200
	v_and_b32_e32 v113, v113, v202
	v_and_b32_e32 v114, v114, v203
	v_and_b32_e32 v115, v115, v204
	v_mfma_f32_16x16x32_bf16 v[136:139], v[92:95], v[116:119], 0
	s_nop 0
	v_mfma_f32_16x16x32_bf16 v[140:143], v[92:95], v[112:115], 0
	v_mul_f32_e32 v112, s54, v124
	v_exp_f32_e32 v112, v112
	v_lshlrev_b32_e32 v113, 16, v72
	v_and_b32_e32 v72, 0xffff0000, v72
	v_lshlrev_b32_e32 v116, 16, v73
	v_mul_f32_e32 v114, s85, v112
	v_mul_f32_e32 v113, v112, v113
	v_mul_f32_e32 v115, s85, v114
	v_mul_f32_e32 v72, v114, v72
	v_cvt_pk_bf16_f32 v72, v113, v72
	v_mul_f32_e32 v113, s85, v115
	v_mul_f32_e32 v114, s85, v113
	v_and_b32_e32 v73, 0xffff0000, v73
	v_mul_f32_e32 v115, v115, v116
	v_mul_f32_e32 v73, v113, v73
	v_mul_f32_e32 v113, s85, v114
	v_lshlrev_b32_e32 v116, 16, v74
	v_and_b32_e32 v74, 0xffff0000, v74
	v_cvt_pk_bf16_f32 v73, v115, v73
	v_mul_f32_e32 v115, s85, v113
	v_mul_f32_e32 v114, v114, v116
	v_mul_f32_e32 v74, v113, v74
	v_cvt_pk_bf16_f32 v74, v114, v74
	v_mul_f32_e32 v113, s85, v115
	v_lshlrev_b32_e32 v114, 16, v75
	v_and_b32_e32 v75, 0xffff0000, v75
	v_mul_f32_e32 v112, s86, v112
	v_mul_f32_e32 v114, v115, v114
	v_mul_f32_e32 v75, v113, v75
	v_mul_f32_e32 v113, s85, v112
	v_cvt_pk_bf16_f32 v75, v114, v75
	v_mul_f32_e32 v114, s85, v113
	v_lshlrev_b32_e32 v115, 16, v80
	v_and_b32_e32 v80, 0xffff0000, v80
	v_mul_f32_e32 v115, v112, v115
	v_mul_f32_e32 v80, v113, v80
	v_mul_f32_e32 v113, s85, v114
	v_cvt_pk_bf16_f32 v80, v115, v80
	v_mul_f32_e32 v115, s85, v113
	v_lshlrev_b32_e32 v116, 16, v81
	v_and_b32_e32 v81, 0xffff0000, v81
	v_mul_f32_e32 v114, v114, v116
	v_mul_f32_e32 v81, v113, v81
	v_mul_f32_e32 v113, s85, v115
	v_lshlrev_b32_e32 v116, 16, v82
	v_and_b32_e32 v82, 0xffff0000, v82
	v_cvt_pk_bf16_f32 v81, v114, v81
	v_mul_f32_e32 v114, s85, v113
	v_mul_f32_e32 v115, v115, v116
	v_mul_f32_e32 v82, v113, v82
	v_cvt_pk_bf16_f32 v82, v115, v82
	v_mul_f32_e32 v113, s85, v114
	v_lshlrev_b32_e32 v115, 16, v83
	v_and_b32_e32 v83, 0xffff0000, v83
	v_mul_f32_e32 v112, s86, v112
	v_mul_f32_e32 v114, v114, v115
	v_mul_f32_e32 v83, v113, v83
	v_mul_f32_e32 v113, s85, v112
	v_cvt_pk_bf16_f32 v83, v114, v83
	v_mul_f32_e32 v114, s85, v113
	v_lshlrev_b32_e32 v115, 16, v88
	v_and_b32_e32 v88, 0xffff0000, v88
	v_mul_f32_e32 v115, v112, v115
	v_mul_f32_e32 v88, v113, v88
	v_mul_f32_e32 v113, s85, v114
	v_cvt_pk_bf16_f32 v88, v115, v88
	v_mul_f32_e32 v115, s85, v113
	v_lshlrev_b32_e32 v116, 16, v89
	v_and_b32_e32 v89, 0xffff0000, v89
	v_mul_f32_e32 v114, v114, v116
	v_mul_f32_e32 v89, v113, v89
	v_mul_f32_e32 v113, s85, v115
	v_lshlrev_b32_e32 v116, 16, v90
	v_and_b32_e32 v90, 0xffff0000, v90
	v_cvt_pk_bf16_f32 v89, v114, v89
	v_mul_f32_e32 v114, s85, v113
	v_mul_f32_e32 v115, v115, v116
	v_mul_f32_e32 v90, v113, v90
	v_cvt_pk_bf16_f32 v90, v115, v90
	v_mul_f32_e32 v113, s85, v114
	v_lshlrev_b32_e32 v115, 16, v91
	v_and_b32_e32 v91, 0xffff0000, v91
	v_mul_f32_e32 v112, s86, v112
	v_mul_f32_e32 v114, v114, v115
	v_mul_f32_e32 v91, v113, v91
	v_mul_f32_e32 v113, s85, v112
	v_lshlrev_b32_e32 v115, 16, v92
	v_and_b32_e32 v92, 0xffff0000, v92
	v_cvt_pk_bf16_f32 v91, v114, v91
	v_mul_f32_e32 v114, s85, v113
	v_mul_f32_e32 v112, v112, v115
	v_mul_f32_e32 v92, v113, v92
	v_cvt_pk_bf16_f32 v92, v112, v92
	v_mul_f32_e32 v112, s85, v114
	v_mul_f32_e32 v113, s85, v112
	v_lshlrev_b32_e32 v115, 16, v93
	v_and_b32_e32 v93, 0xffff0000, v93
	v_mul_f32_e32 v114, v114, v115
	v_mul_f32_e32 v93, v112, v93
	v_mul_f32_e32 v112, s85, v113
	v_lshlrev_b32_e32 v115, 16, v94
	v_and_b32_e32 v94, 0xffff0000, v94
	v_cvt_pk_bf16_f32 v93, v114, v93
	v_mul_f32_e32 v114, s85, v112
	v_mul_f32_e32 v113, v113, v115
	v_mul_f32_e32 v94, v112, v94
	v_cvt_pk_bf16_f32 v94, v113, v94
	v_mul_f32_e32 v112, s85, v114
	v_lshlrev_b32_e32 v113, 16, v95
	v_and_b32_e32 v95, 0xffff0000, v95
	v_mul_f32_e32 v113, v114, v113
	v_mul_f32_e32 v95, v112, v95
	v_cvt_pk_bf16_f32 v95, v113, v95
	v_add_u32_e32 v223, v163, v164
	v_add_u32_e32 v224, v163, v165
	v_cvt_pk_bf16_f32 v228, v44, v45
	v_cvt_pk_bf16_f32 v229, v46, v47
	v_cvt_pk_bf16_f32 v230, v40, v41
	v_cvt_pk_bf16_f32 v231, v42, v43
	v_cvt_pk_bf16_f32 v242, v36, v37
	v_cvt_pk_bf16_f32 v243, v38, v39
	v_cvt_pk_bf16_f32 v244, v32, v33
	v_cvt_pk_bf16_f32 v245, v34, v35
	ds_read_b64 v[112:113], v223
	ds_read_b64 v[114:115], v224
	v_add_u32_e32 v225, v163, v166
	v_add_u32_e32 v226, v163, v167
	ds_read_b64 v[116:117], v225
	ds_read_b64 v[118:119], v226
	ds_read_b64 v[120:121], v223 offset:2048
	ds_read_b64 v[122:123], v224 offset:2048
	ds_read_b64 v[124:125], v225 offset:2048
	ds_read_b64 v[126:127], v226 offset:2048
	s_waitcnt lgkmcnt(6)
	v_mfma_f32_16x16x32_bf16 v[64:67], v[228:231], v[112:115], v[64:67]
	s_waitcnt lgkmcnt(4)
	v_mfma_f32_16x16x32_bf16 v[112:115], v[242:245], v[116:119], v[64:67]
	s_nop 5
	ds_read_b64 v[64:65], v223 offset:4096
	ds_read_b64 v[66:67], v224 offset:4096
	ds_read_b64 v[246:247], v225 offset:4096
	ds_read_b64 v[248:249], v226 offset:4096
	s_waitcnt lgkmcnt(6)
	v_mfma_f32_16x16x32_bf16 v[68:71], v[228:231], v[120:123], v[68:71]
	s_waitcnt lgkmcnt(4)
	v_mfma_f32_16x16x32_bf16 v[116:119], v[242:245], v[124:127], v[68:71]
	s_nop 5
	ds_read_b64 v[68:69], v223 offset:6144
	ds_read_b64 v[70:71], v224 offset:6144
	ds_read_b64 v[124:125], v225 offset:6144
	ds_read_b64 v[126:127], v226 offset:6144
	s_waitcnt lgkmcnt(6)
	v_mfma_f32_16x16x32_bf16 v[64:67], v[228:231], v[64:67], v[76:79]
	s_waitcnt lgkmcnt(4)
; __device__ __forceinline__ bf16x8 pack8(s16x4 lo, s16x4 hi) { return (bf16x8){lo[0], lo[1], lo[2], lo[3], hi[0], hi[1], hi[2], hi[3]}; }
; #define SCAN_LOAD_QK(cc, pq) do { const size_t u0_ = (rb + (size_t)(cc) * 128) * 2048 + head * 256 + (pq) * 64;     \
;             _Pragma("unroll") for (int ii = 0; ii < 2; ++ii) { rq[ii] = *(const GAS u32x4*)(Q + u0_ + (size_t)ii * 64 * 2048 + lqk_l); rk[ii] = *(const GAS u32x4*)(K + u0_ + (size_t)ii * 64 * 2048 + lqk_l); } } while (0)
; #define SCAN_WRITE_QK(par) do { _Pragma("unroll") for (int ii = 0; ii < 2; ++ii) { *(LAS u32x4*)(bSt + ((par) ? LQ1 : LQ0) + ii * 64 * QS) = rq[ii]; *(LAS u32x4*)(bSt + ((par) ? LK1 : LK0) + ii * 64 * QS) = rk[ii]; } } while (0)
; #define SCAN_KREAD(b_, mt_) do { _Pragma("unroll") for (int ks = 0; ks < 4; ++ks) { const int ko = ((p & 1) ? LK1 : LK0) + 32 * ks * QS; kl[b_][ks] = tr_read(bKlo[mt_] + ko); kh[b_][ks] = tr_read(bKhi[mt_] + ko); } } while (0)
; __device__ __forceinline__ void scan_phase(const Frame& F, const bf16_t* Q, const bf16_t* K, const bf16_t* V, const bf16_t* PB, bf16_t* OF, bf16_t* OB, int half) {
;     ...
;                 if (p < 3 || more) SCAN_WRITE_QK((p + 1) & 1);
;                 if (p == 1 && more) SCAN_DMA_VP(cn);
;                 if (p < 2) SCAN_LOAD_QK(c, p + 2); else if (more) SCAN_LOAD_QK(cn, p - 2);
;     ...
;                 { s16x4 kl[2][4], kh[2][4];
;     ...
;                 SCAN_KREAD(0, 0);
; #pragma unroll
;                 for (int mt = 0; mt < 4; ++mt) { if (mt < 3) SCAN_KREAD((mt + 1) & 1, mt + 1);
;                     f32x4 acc = Rt[4 * p + mt] * c1;
; #pragma unroll
;                     for (int ks = 0; ks < 4; ++ks) acc = __builtin_amdgcn_mfma_f32_16x16x32_bf16(pack8(kl[mt & 1][ks], kh[mt & 1][ks]), Vf[ks], acc, 0, 0, 0);
;                     Rt[4 * p + mt] = acc; }
	v_mfma_f32_16x16x32_bf16 v[120:123], v[242:245], v[246:249], v[64:67]
	s_nop 5
	ds_read_b64 v[64:65], v223 offset:8192
	ds_read_b64 v[66:67], v224 offset:8192
	ds_read_b64 v[76:77], v225 offset:8192
	ds_read_b64 v[78:79], v226 offset:8192
	s_waitcnt lgkmcnt(6)
	v_mfma_f32_16x16x32_bf16 v[68:71], v[228:231], v[68:71], v[84:87]
	s_waitcnt lgkmcnt(4)
	v_mfma_f32_16x16x32_bf16 v[124:127], v[242:245], v[124:127], v[68:71]
	s_nop 5
	ds_read_b64 v[68:69], v223 offset:10240
	ds_read_b64 v[70:71], v224 offset:10240
	ds_read_b64 v[84:85], v225 offset:10240
	ds_read_b64 v[86:87], v226 offset:10240
	s_waitcnt lgkmcnt(6)
	v_mfma_f32_16x16x32_bf16 v[64:67], v[228:231], v[64:67], v[128:131]
	s_waitcnt lgkmcnt(4)
	v_mfma_f32_16x16x32_bf16 v[128:131], v[242:245], v[76:79], v[64:67]
	s_nop 5
	ds_read_b64 v[64:65], v223 offset:12288
	ds_read_b64 v[66:67], v224 offset:12288
	ds_read_b64 v[76:77], v225 offset:12288
	ds_read_b64 v[78:79], v226 offset:12288
	s_waitcnt lgkmcnt(6)
	v_mfma_f32_16x16x32_bf16 v[68:71], v[228:231], v[68:71], v[132:135]
	s_waitcnt lgkmcnt(4)
	v_mfma_f32_16x16x32_bf16 v[132:135], v[242:245], v[84:87], v[68:71]
	s_nop 5
	ds_read_b64 v[68:69], v223 offset:14336
	ds_read_b64 v[70:71], v224 offset:14336
	ds_read_b64 v[84:85], v225 offset:14336
	ds_read_b64 v[86:87], v226 offset:14336
	s_waitcnt lgkmcnt(6)
	v_mfma_f32_16x16x32_bf16 v[64:67], v[228:231], v[64:67], v[136:139]
	s_waitcnt lgkmcnt(4)
	v_mfma_f32_16x16x32_bf16 v[136:139], v[242:245], v[76:79], v[64:67]
	s_waitcnt lgkmcnt(2)
	v_mfma_f32_16x16x32_bf16 v[64:67], v[228:231], v[68:71], v[140:143]
	s_waitcnt lgkmcnt(0)
	v_mfma_f32_16x16x32_bf16 v[140:143], v[242:245], v[84:87], v[64:67]
	v_add_u32_e32 v227, v182, v189
	v_add_u32_e32 v228, v182, v190
	s_nop 3
	ds_read_b64_tr_b16 v[64:65], v227 offset:32768
	ds_read_b64_tr_b16 v[66:67], v228 offset:33280
	ds_read_b64_tr_b16 v[68:69], v227 offset:36864
	ds_read_b64_tr_b16 v[70:71], v228 offset:37376
	v_mov_b32_e32 v145, v144
	ds_read_b64_tr_b16 v[76:77], v227 offset:40960
	ds_read_b64_tr_b16 v[78:79], v228 offset:41472
	v_add_u32_e32 v229, v182, v187
	v_add_u32_e32 v230, v182, v188
	v_pk_mul_f32 v[46:47], v[144:145], v[46:47]
	v_pk_mul_f32 v[44:45], v[146:147], v[44:45]
	ds_read_b64_tr_b16 v[84:85], v227 offset:45056
	ds_read_b64_tr_b16 v[86:87], v228 offset:45568
	ds_read_b64_tr_b16 v[242:243], v229 offset:32768
	ds_read_b64_tr_b16 v[244:245], v230 offset:33280
	ds_read_b64_tr_b16 v[246:247], v229 offset:36864
	ds_read_b64_tr_b16 v[248:249], v230 offset:37376
	ds_read_b64_tr_b16 v[194:195], v229 offset:40960
	ds_read_b64_tr_b16 v[196:197], v230 offset:41472
	ds_read_b64_tr_b16 v[238:239], v229 offset:45056
	ds_read_b64_tr_b16 v[240:241], v230 offset:45568
	s_waitcnt lgkmcnt(14)
	v_mfma_f32_16x16x32_bf16 v[44:47], v[64:67], v[72:75], v[44:47]
	v_add_u32_e32 v231, v182, v185
	v_add_u32_e32 v232, v182, v186
	v_pk_mul_f32 v[42:43], v[144:145], v[42:43]
	s_waitcnt lgkmcnt(12)
	v_mfma_f32_16x16x32_bf16 v[44:47], v[68:71], v[80:83], v[44:47]
	v_mul_f32_e64 v40, v146, v40
	v_mul_f32_e64 v41, v147, v41
	v_add_u32_e32 v233, v182, v183
	v_pk_mul_f32 v[38:39], v[144:145], v[38:39]
	s_waitcnt lgkmcnt(10)
	v_mfma_f32_16x16x32_bf16 v[44:47], v[76:79], v[88:91], v[44:47]
	v_mul_f32_e64 v36, v146, v36
	v_mul_f32_e64 v37, v147, v37
	v_pk_mul_f32 v[34:35], v[144:145], v[34:35]
	v_pk_mul_f32 v[32:33], v[146:147], v[32:33]
	s_waitcnt lgkmcnt(8)
	v_mfma_f32_16x16x32_bf16 v[44:47], v[84:87], v[92:95], v[44:47]
	ds_read_b64_tr_b16 v[64:65], v231 offset:32768
	ds_read_b64_tr_b16 v[66:67], v232 offset:33280
	ds_read_b64_tr_b16 v[68:69], v231 offset:36864
	ds_read_b64_tr_b16 v[70:71], v232 offset:37376
	ds_read_b64_tr_b16 v[76:77], v231 offset:40960
	ds_read_b64_tr_b16 v[78:79], v232 offset:41472
	ds_read_b64_tr_b16 v[84:85], v231 offset:45056
	ds_read_b64_tr_b16 v[86:87], v232 offset:45568
	s_waitcnt lgkmcnt(14)
	v_mfma_f32_16x16x32_bf16 v[40:43], v[242:245], v[72:75], v[40:43]
	s_waitcnt lgkmcnt(12)
	v_mfma_f32_16x16x32_bf16 v[40:43], v[246:249], v[80:83], v[40:43]
	s_waitcnt lgkmcnt(10)
	v_mfma_f32_16x16x32_bf16 v[40:43], v[194:197], v[88:91], v[40:43]
	s_waitcnt lgkmcnt(8)
	v_mfma_f32_16x16x32_bf16 v[40:43], v[238:241], v[92:95], v[40:43]
	v_add_u32_e32 v241, v182, v184
	ds_read_b64_tr_b16 v[194:195], v233 offset:32768
	ds_read_b64_tr_b16 v[196:197], v241 offset:33280
	ds_read_b64_tr_b16 v[242:243], v233 offset:36864
	ds_read_b64_tr_b16 v[244:245], v241 offset:37376
	ds_read_b64_tr_b16 v[246:247], v233 offset:40960
	ds_read_b64_tr_b16 v[248:249], v241 offset:41472
	ds_read_b64_tr_b16 v[234:235], v233 offset:45056
	ds_read_b64_tr_b16 v[236:237], v241 offset:45568
	s_waitcnt lgkmcnt(14)
	v_mfma_f32_16x16x32_bf16 v[36:39], v[64:67], v[72:75], v[36:39]
	s_waitcnt lgkmcnt(0)
	s_barrier
	s_waitcnt vmcnt(3)
	ds_write_b128 v214, v[96:99]
	s_waitcnt vmcnt(2)
	ds_write_b128 v214, v[100:103] offset:32768
	s_waitcnt lgkmcnt(14)
	v_mfma_f32_16x16x32_bf16 v[36:39], v[68:71], v[80:83], v[36:39]
	s_waitcnt vmcnt(1)
	ds_write_b128 v214, v[104:107] offset:8192
	s_waitcnt vmcnt(0)
	ds_write_b128 v214, v[108:111] offset:40960
	s_waitcnt lgkmcnt(14)
	v_mfma_f32_16x16x32_bf16 v[36:39], v[76:79], v[88:91], v[36:39]
	s_waitcnt lgkmcnt(12)
	v_mfma_f32_16x16x32_bf16 v[36:39], v[84:87], v[92:95], v[36:39]
	s_waitcnt lgkmcnt(10)
	v_mfma_f32_16x16x32_bf16 v[32:35], v[194:197], v[72:75], v[32:35]
	s_waitcnt lgkmcnt(8)
	v_mfma_f32_16x16x32_bf16 v[32:35], v[242:245], v[80:83], v[32:35]
	s_waitcnt lgkmcnt(6)
	v_mfma_f32_16x16x32_bf16 v[32:35], v[246:249], v[88:91], v[32:35]
	s_waitcnt lgkmcnt(4)
	v_mfma_f32_16x16x32_bf16 v[32:35], v[234:237], v[92:95], v[32:35]
	v_add_co_u32_e32 v64, vcc, 0x10780000, v158
	s_nop 1
	v_addc_co_u32_e32 v65, vcc, 0, v159, vcc
	v_add_co_u32_e32 v68, vcc, 0x4a880000, v156
	global_load_dwordx4 v[64:67], v[64:65], off offset:384
	s_nop 0
	v_addc_co_u32_e32 v69, vcc, 0, v157, vcc
	v_add_co_u32_e32 v76, vcc, 0x107c0000, v158
	global_load_dwordx4 v[68:71], v[68:69], off offset:384
	s_nop 0
	v_addc_co_u32_e32 v77, vcc, 0, v159, vcc
	v_add_co_u32_e32 v84, vcc, 0x4a8c0000, v156
	global_load_dwordx4 v[76:79], v[76:77], off offset:384
	s_nop 0
	v_addc_co_u32_e32 v85, vcc, 0, v157, vcc
	global_load_dwordx4 v[84:87], v[84:85], off offset:384
	s_cbranch_scc1 .LBB0_980
; __device__ __forceinline__ void scan_phase(const Frame& F, const bf16_t* Q, const bf16_t* K, const bf16_t* V, const bf16_t* PB, bf16_t* OF, bf16_t* OB, int half) {
;     ...
;                 if (p == 1 && more) SCAN_DMA_VP(cn);
	s_add_u32 s12, s90, s40
	s_addc_u32 s13, s91, s41
	s_ashr_i32 s39, s38, 31
	s_lshl_b64 s[34:35], s[38:39], 18
	s_add_u32 s34, s88, s34
	s_mov_b32 s39, m0
	s_mov_b32 m0, s74
	s_nop 0
	global_load_lds_dwordx4 v215, s[12:13]
	s_mov_b32 m0, s39
	s_addc_u32 s35, s89, s35
	s_mov_b32 s39, m0
	s_mov_b32 m0, s75
	s_nop 0
	global_load_lds_dwordx4 v216, s[34:35]
	s_mov_b32 m0, s39
	s_nop 0
	s_mov_b32 s39, m0
	s_mov_b32 m0, s79
	s_nop 0
	global_load_lds_dwordx4 v217, s[12:13]
	s_mov_b32 m0, s39
	s_nop 0
	s_mov_b32 s39, m0
	s_mov_b32 m0, s80
	s_nop 0
	global_load_lds_dwordx4 v218, s[34:35]
	s_mov_b32 m0, s39
	s_nop 0
	s_mov_b32 s39, m0
	s_mov_b32 m0, s81
	s_nop 0
	global_load_lds_dwordx4 v219, s[12:13]
	s_mov_b32 m0, s39
	s_nop 0
	s_mov_b32 s39, m0
	s_mov_b32 m0, s82
	s_nop 0
	global_load_lds_dwordx4 v220, s[34:35]
	s_mov_b32 m0, s39
	s_nop 0
	s_mov_b32 s39, m0
	s_mov_b32 m0, s83
	s_nop 0
	global_load_lds_dwordx4 v221, s[12:13]
	s_mov_b32 m0, s39
	s_mov_b32 s12, m0
	s_mov_b32 m0, s84
	s_nop 0
	global_load_lds_dwordx4 v222, s[34:35]
	s_mov_b32 m0, s12
; __device__ __forceinline__ void scan_phase(const Frame& F, const bf16_t* Q, const bf16_t* K, const bf16_t* V, const bf16_t* PB, bf16_t* OF, bf16_t* OB, int half) {
;     ...
;                 {
;                     bf16x8 Rf[2];
; #pragma unroll
;                     for (int ks = 0; ks < 2; ++ks) { const f32x4 r0v = Rt[4 * p + 2 * ks], r1v = Rt[4 * p + 2 * ks + 1];
;                         const u32x4 wvv = {cvt_pk_bf16(r0v[0], r0v[1]), cvt_pk_bf16(r0v[2], r0v[3]), cvt_pk_bf16(r1v[0], r1v[1]), cvt_pk_bf16(r1v[2], r1v[3])};
;                         Rf[ks] = __builtin_bit_cast(bf16x8, wvv); }
;                     u32x4 qf[2][2];
;     ...
;                     SCAN_QREAD(0, 0);
; #pragma unroll
;                     for (int it = 0; it < 8; ++it) { if (it < 7) SCAN_QREAD((it + 1) & 1, it + 1);
; #pragma unroll
;                         for (int ks = 0; ks < 2; ++ks) Ot[it] = __builtin_amdgcn_mfma_f32_16x16x32_bf16(Rf[ks], __builtin_bit_cast(bf16x8, qf[it & 1][ks]), Ot[it], 0, 0, 0); }
;     ...
;                     __builtin_amdgcn_sched_group_barrier(0x100, 4, 0);
;                     __builtin_amdgcn_sched_group_barrier(0x100, 4, 0); __builtin_amdgcn_sched_group_barrier(0x8, 2, 0);
;                     __builtin_amdgcn_sched_group_barrier(0x100, 4, 0); __builtin_amdgcn_sched_group_barrier(0x8, 2, 0);
;                     __builtin_amdgcn_sched_group_barrier(0x100, 4, 0); __builtin_amdgcn_sched_group_barrier(0x8, 2, 0);
;                     __builtin_amdgcn_sched_group_barrier(0x100, 4, 0); __builtin_amdgcn_sched_group_barrier(0x8, 2, 0);
;                     __builtin_amdgcn_sched_group_barrier(0x100, 4, 0); __builtin_amdgcn_sched_group_barrier(0x8, 2, 0);
;                     __builtin_amdgcn_sched_group_barrier(0x100, 4, 0); __builtin_amdgcn_sched_group_barrier(0x8, 2, 0);
;                     __builtin_amdgcn_sched_group_barrier(0x100, 4, 0); __builtin_amdgcn_sched_group_barrier(0x8, 2, 0);
;                     __builtin_amdgcn_sched_group_barrier(0x8, 2, 0);
;                 }
;                 __builtin_amdgcn_sched_barrier(0);
;                 { s16x4 kl[2][4], kh[2][4];
;     ...
;                 SCAN_KREAD(0, 0);
; #pragma unroll
;                 for (int mt = 0; mt < 4; ++mt) { if (mt < 3) SCAN_KREAD((mt + 1) & 1, mt + 1);
;                     f32x4 acc = Rt[4 * p + mt] * c1;
; #pragma unroll
.LBB0_980:
	v_cvt_pk_bf16_f32 v156, v28, v29
	v_cvt_pk_bf16_f32 v157, v30, v31
	v_cvt_pk_bf16_f32 v158, v20, v21
	v_cvt_pk_bf16_f32 v159, v22, v23
	v_cvt_pk_bf16_f32 v194, v16, v17
	v_cvt_pk_bf16_f32 v195, v18, v19
	v_cvt_pk_bf16_f32 v196, v24, v25
	v_cvt_pk_bf16_f32 v197, v26, v27
	ds_read_b64 v[96:97], v223 offset:16384
	ds_read_b64 v[98:99], v224 offset:16384
	ds_read_b64 v[100:101], v225 offset:16384
	ds_read_b64 v[102:103], v226 offset:16384
	ds_read_b64 v[104:105], v223 offset:18432
	ds_read_b64 v[106:107], v224 offset:18432
	ds_read_b64 v[108:109], v225 offset:18432
	ds_read_b64 v[110:111], v226 offset:18432
	s_waitcnt lgkmcnt(6)
	v_mfma_f32_16x16x32_bf16 v[96:99], v[156:159], v[96:99], v[112:115]
	s_waitcnt lgkmcnt(4)
	v_mfma_f32_16x16x32_bf16 v[96:99], v[194:197], v[100:103], v[96:99]
	s_nop 0
	ds_read_b64 v[112:113], v223 offset:20480
	ds_read_b64 v[114:115], v224 offset:20480
	ds_read_b64 v[234:235], v225 offset:20480
	ds_read_b64 v[236:237], v226 offset:20480
	s_waitcnt lgkmcnt(6)
	v_mfma_f32_16x16x32_bf16 v[100:103], v[156:159], v[104:107], v[116:119]
	s_waitcnt lgkmcnt(4)
	v_mfma_f32_16x16x32_bf16 v[100:103], v[194:197], v[108:111], v[100:103]
	ds_read_b64 v[108:109], v223 offset:22528
	ds_read_b64 v[110:111], v224 offset:22528
	ds_read_b64 v[116:117], v225 offset:22528
	ds_read_b64 v[118:119], v226 offset:22528
	s_waitcnt lgkmcnt(6)
	v_mfma_f32_16x16x32_bf16 v[104:107], v[156:159], v[112:115], v[120:123]
	s_waitcnt lgkmcnt(4)
	v_mfma_f32_16x16x32_bf16 v[104:107], v[194:197], v[234:237], v[104:107]
	ds_read_b64 v[112:113], v223 offset:24576
	ds_read_b64 v[114:115], v224 offset:24576
	ds_read_b64 v[120:121], v225 offset:24576
	ds_read_b64 v[122:123], v226 offset:24576
	s_waitcnt lgkmcnt(6)
	v_mfma_f32_16x16x32_bf16 v[108:111], v[156:159], v[108:111], v[124:127]
	s_waitcnt lgkmcnt(4)
	v_mfma_f32_16x16x32_bf16 v[108:111], v[194:197], v[116:119], v[108:111]
	ds_read_b64 v[116:117], v223 offset:26624
	ds_read_b64 v[118:119], v224 offset:26624
	ds_read_b64 v[124:125], v225 offset:26624
	ds_read_b64 v[126:127], v226 offset:26624
	s_waitcnt lgkmcnt(6)
	v_mfma_f32_16x16x32_bf16 v[112:115], v[156:159], v[112:115], v[128:131]
	s_waitcnt lgkmcnt(4)
	v_mfma_f32_16x16x32_bf16 v[112:115], v[194:197], v[120:123], v[112:115]
	ds_read_b64 v[120:121], v223 offset:28672
	ds_read_b64 v[122:123], v224 offset:28672
	ds_read_b64 v[128:129], v225 offset:28672
	ds_read_b64 v[130:131], v226 offset:28672
	s_waitcnt lgkmcnt(6)
	v_mfma_f32_16x16x32_bf16 v[116:119], v[156:159], v[116:119], v[132:135]
	s_waitcnt lgkmcnt(4)
	v_mfma_f32_16x16x32_bf16 v[116:119], v[194:197], v[124:127], v[116:119]
	ds_read_b64 v[124:125], v223 offset:30720
	ds_read_b64 v[126:127], v224 offset:30720
	ds_read_b64 v[132:133], v225 offset:30720
	ds_read_b64 v[134:135], v226 offset:30720
	s_waitcnt lgkmcnt(6)
	v_mfma_f32_16x16x32_bf16 v[120:123], v[156:159], v[120:123], v[136:139]
	s_waitcnt lgkmcnt(4)
	v_mfma_f32_16x16x32_bf16 v[120:123], v[194:197], v[128:131], v[120:123]
	s_waitcnt lgkmcnt(2)
	v_mfma_f32_16x16x32_bf16 v[124:127], v[156:159], v[124:127], v[140:143]
	s_waitcnt lgkmcnt(0)
	v_mfma_f32_16x16x32_bf16 v[124:127], v[194:197], v[132:135], v[124:127]
	ds_read_b64_tr_b16 v[128:129], v227 offset:49152
	ds_read_b64_tr_b16 v[130:131], v228 offset:49664
	ds_read_b64_tr_b16 v[132:133], v227 offset:53248
	ds_read_b64_tr_b16 v[134:135], v228 offset:53760
	ds_read_b64_tr_b16 v[136:137], v227 offset:57344
	ds_read_b64_tr_b16 v[138:139], v228 offset:57856
	v_pk_mul_f32 v[30:31], v[144:145], v[30:31]
	v_pk_mul_f32 v[28:29], v[146:147], v[28:29]
	ds_read_b64_tr_b16 v[140:141], v227 offset:61440
	ds_read_b64_tr_b16 v[142:143], v228 offset:61952
	ds_read_b64_tr_b16 v[156:157], v229 offset:49152
	ds_read_b64_tr_b16 v[158:159], v230 offset:49664
	ds_read_b64_tr_b16 v[194:195], v229 offset:53248
	ds_read_b64_tr_b16 v[196:197], v230 offset:53760
	ds_read_b64_tr_b16 v[234:235], v229 offset:57344
	ds_read_b64_tr_b16 v[236:237], v230 offset:57856
	ds_read_b64_tr_b16 v[242:243], v229 offset:61440
	ds_read_b64_tr_b16 v[244:245], v230 offset:61952
	s_waitcnt lgkmcnt(14)
	v_mfma_f32_16x16x32_bf16 v[28:31], v[128:131], v[72:75], v[28:31]
	v_mul_f32_e64 v22, v144, v22
	v_mul_f32_e64 v23, v145, v23
	v_pk_mul_f32 v[20:21], v[146:147], v[20:21]
	v_pk_mul_f32 v[18:19], v[144:145], v[18:19]
	s_waitcnt lgkmcnt(12)
	v_mfma_f32_16x16x32_bf16 v[28:31], v[132:135], v[80:83], v[28:31]
	v_mul_f32_e64 v16, v146, v16
	v_mul_f32_e64 v17, v147, v17
	v_pk_mul_f32 v[26:27], v[144:145], v[26:27]
	v_pk_mul_f32 v[24:25], v[146:147], v[24:25]
	s_waitcnt lgkmcnt(10)
	v_mfma_f32_16x16x32_bf16 v[28:31], v[136:139], v[88:91], v[28:31]
	s_andn2_b64 vcc, exec, s[44:45]
	s_waitcnt lgkmcnt(8)
	v_mfma_f32_16x16x32_bf16 v[28:31], v[140:143], v[92:95], v[28:31]
	ds_read_b64_tr_b16 v[128:129], v231 offset:49152
	ds_read_b64_tr_b16 v[130:131], v232 offset:49664
	ds_read_b64_tr_b16 v[132:133], v231 offset:53248
	ds_read_b64_tr_b16 v[134:135], v232 offset:53760
	ds_read_b64_tr_b16 v[136:137], v231 offset:57344
	ds_read_b64_tr_b16 v[138:139], v232 offset:57856
	ds_read_b64_tr_b16 v[140:141], v231 offset:61440
	ds_read_b64_tr_b16 v[142:143], v232 offset:61952
	s_waitcnt lgkmcnt(14)
	v_mfma_f32_16x16x32_bf16 v[20:23], v[156:159], v[72:75], v[20:23]
	s_waitcnt lgkmcnt(12)
	v_mfma_f32_16x16x32_bf16 v[20:23], v[194:197], v[80:83], v[20:23]
	s_waitcnt lgkmcnt(10)
	v_mfma_f32_16x16x32_bf16 v[20:23], v[234:237], v[88:91], v[20:23]
	s_waitcnt lgkmcnt(8)
	v_mfma_f32_16x16x32_bf16 v[20:23], v[242:245], v[92:95], v[20:23]
	ds_read_b64_tr_b16 v[156:157], v233 offset:49152
	ds_read_b64_tr_b16 v[158:159], v241 offset:49664
	ds_read_b64_tr_b16 v[194:195], v233 offset:53248
	ds_read_b64_tr_b16 v[196:197], v241 offset:53760
	ds_read_b64_tr_b16 v[234:235], v233 offset:57344
	ds_read_b64_tr_b16 v[236:237], v241 offset:57856
	ds_read_b64_tr_b16 v[242:243], v233 offset:61440
	ds_read_b64_tr_b16 v[244:245], v241 offset:61952
	s_waitcnt lgkmcnt(14)
	v_mfma_f32_16x16x32_bf16 v[16:19], v[128:131], v[72:75], v[16:19]
	s_waitcnt lgkmcnt(0)
	s_barrier
	v_cndmask_b32_e64 v128, 0, 1, s[44:45]
	v_cmp_ne_u32_e64 s[34:35], 1, v128
	s_waitcnt lgkmcnt(12)
	v_mfma_f32_16x16x32_bf16 v[16:19], v[132:135], v[80:83], v[16:19]
	v_lshl_add_u64 v[128:129], v[148:149], 0, s[42:43]
	v_lshl_add_u64 v[130:131], v[150:151], 0, s[42:43]
	s_cbranch_vccnz .Lscan0_nodma
	s_waitcnt vmcnt(8)
	s_branch .Lscan0_wdone

; __device__ __forceinline__ bf16x8 pack8(s16x4 lo, s16x4 hi) { return (bf16x8){lo[0], lo[1], lo[2], lo[3], hi[0], hi[1], hi[2], hi[3]}; }
; #define SCAN_LOAD_QK(cc, pq) do { const size_t u0_ = (rb + (size_t)(cc) * 128) * 2048 + head * 256 + (pq) * 64;     \
;             _Pragma("unroll") for (int ii = 0; ii < 2; ++ii) { rq[ii] = *(const GAS u32x4*)(Q + u0_ + (size_t)ii * 64 * 2048 + lqk_l); rk[ii] = *(const GAS u32x4*)(K + u0_ + (size_t)ii * 64 * 2048 + lqk_l); } } while (0)
; #define SCAN_WRITE_QK(par) do { _Pragma("unroll") for (int ii = 0; ii < 2; ++ii) { *(LAS u32x4*)(bSt + ((par) ? LQ1 : LQ0) + ii * 64 * QS) = rq[ii]; *(LAS u32x4*)(bSt + ((par) ? LK1 : LK0) + ii * 64 * QS) = rk[ii]; } } while (0)
; #define SCAN_KREAD(b_, mt_) do { _Pragma("unroll") for (int ks = 0; ks < 4; ++ks) { const int ko = ((p & 1) ? LK1 : LK0) + 32 * ks * QS; kl[b_][ks] = tr_read(bKlo[mt_] + ko); kh[b_][ks] = tr_read(bKhi[mt_] + ko); } } while (0)
; __device__ __forceinline__ void scan_phase(const Frame& F, const bf16_t* Q, const bf16_t* K, const bf16_t* V, const bf16_t* PB, bf16_t* OF, bf16_t* OB, int half) {
;     ...
;                 if (p < 3 || more) SCAN_WRITE_QK((p + 1) & 1);
;                 if (p == 1 && more) SCAN_DMA_VP(cn);
;                 if (p < 2) SCAN_LOAD_QK(c, p + 2); else if (more) SCAN_LOAD_QK(cn, p - 2);
;     ...
;                 { s16x4 kl[2][4], kh[2][4];
;     ...
;                 SCAN_KREAD(0, 0);
; #pragma unroll
;                 for (int mt = 0; mt < 4; ++mt) { if (mt < 3) SCAN_KREAD((mt + 1) & 1, mt + 1);
;                     f32x4 acc = Rt[4 * p + mt] * c1;
; #pragma unroll
;                     for (int ks = 0; ks < 4; ++ks) acc = __builtin_amdgcn_mfma_f32_16x16x32_bf16(pack8(kl[mt & 1][ks], kh[mt & 1][ks]), Vf[ks], acc, 0, 0, 0);
;                     Rt[4 * p + mt] = acc; }
.Lscan0_wdone:
	ds_write_b128 v214, v[64:67] offset:16384
	s_waitcnt lgkmcnt(11)
	v_mfma_f32_16x16x32_bf16 v[16:19], v[136:139], v[88:91], v[16:19]
	ds_write_b128 v214, v[68:71] offset:49152
	ds_write_b128 v214, v[76:79] offset:24576
	ds_write_b128 v214, v[84:87] offset:57344
	s_waitcnt lgkmcnt(12)
	v_mfma_f32_16x16x32_bf16 v[16:19], v[140:143], v[92:95], v[16:19]
	s_waitcnt lgkmcnt(10)
	v_mfma_f32_16x16x32_bf16 v[24:27], v[156:159], v[72:75], v[24:27]
	s_waitcnt lgkmcnt(8)
	v_mfma_f32_16x16x32_bf16 v[24:27], v[194:197], v[80:83], v[24:27]
	s_waitcnt lgkmcnt(6)
	v_mfma_f32_16x16x32_bf16 v[24:27], v[234:237], v[88:91], v[24:27]
	s_waitcnt lgkmcnt(4)
	v_mfma_f32_16x16x32_bf16 v[24:27], v[242:245], v[92:95], v[24:27]
	s_cbranch_vccnz .LBB0_982
	v_add_co_u32_e32 v64, vcc, 0x10700000, v130
	s_nop 1
	v_addc_co_u32_e32 v65, vcc, 0, v131, vcc
	v_add_co_u32_e32 v68, vcc, 0x4a800000, v128
	global_load_dwordx4 v[64:67], v[64:65], off
	s_nop 0
	v_addc_co_u32_e32 v69, vcc, 0, v129, vcc
	v_add_co_u32_e32 v76, vcc, 0x10740000, v130
	global_load_dwordx4 v[68:71], v[68:69], off
	s_nop 0
	v_addc_co_u32_e32 v77, vcc, 0, v131, vcc
	v_add_co_u32_e32 v84, vcc, 0x4a840000, v128
	global_load_dwordx4 v[76:79], v[76:77], off
	s_nop 0
	v_addc_co_u32_e32 v85, vcc, 0, v129, vcc
	global_load_dwordx4 v[84:87], v[84:85], off

; #define LAS __attribute__((address_space(3)))
; __device__ __forceinline__ s16x4 tr_read(LAS unsigned char* p) { return __builtin_bit_cast(s16x4, __builtin_amdgcn_ds_read_tr16_b64_v4i16((LAS v4i16_t*)p)); }
; __device__ __forceinline__ bf16x8 pack8(s16x4 lo, s16x4 hi) { return (bf16x8){lo[0], lo[1], lo[2], lo[3], hi[0], hi[1], hi[2], hi[3]}; }
; template <int M, int N, class Fn> __device__ __forceinline__ void mattn_sfor(Fn&& f) { if constexpr (M < N) { f(std::integral_constant<int, M>{}); mattn_sfor<M + 1, N>(f); } }
; __device__ __forceinline__ void scan_phase(const Frame& F, const bf16_t* Q, const bf16_t* K, const bf16_t* V, const bf16_t* PB, bf16_t* OF, bf16_t* OB, int half) {
;     ...
;             for (int p = 0; p < 4; ++p) {
;                 if (p < 3 || more) SCAN_WRITE_QK((p + 1) & 1);
;                 if (p == 1 && more) SCAN_DMA_VP(cn);
;                 if (p < 2) SCAN_LOAD_QK(c, p + 2); else if (more) SCAN_LOAD_QK(cn, p - 2);
;                 if (p == 0) {
; #pragma unroll
;                     for (int ks = 0; ks < 4; ++ks) { const s16x4 lo = tr_read(bVlo + 32 * ks * 256), hi = tr_read(bVhi + 32 * ks * 256); Vf[ks] = pack8(lo, hi); }
;                     __builtin_amdgcn_sched_barrier(0);
;                     { u32x4 pwb[2];
;                       { constexpr int q0_ = pv_pair(dir, 0); pwb[0] = *(const LAS u32x4*)(bPk[q0_ & 3] + 16 * (q0_ >> 2) * 256); }
;                       __builtin_amdgcn_sched_group_barrier(0x100, 1, 0);
;                       mattn_sfor<0, 20>([&](auto n_) { constexpr int n = decltype(n_)::value, pr = pv_pair(dir, n), it = pr >> 2, ks = pr & 3, dks = ks - (it >> 1);
;                           if constexpr (n + 1 < 20) { constexpr int nx = pv_pair(dir, n + 1); pwb[(n + 1) & 1] = *(const LAS u32x4*)(bPk[nx & 3] + 16 * (nx >> 2) * 256); }
;                           u32x4 pw = pwb[n & 1];
;                           if constexpr (dks == 0) { pw.x &= pmk[it & 1][0]; pw.y &= pmk[it & 1][1]; pw.z &= pmk[it & 1][2]; pw.w &= pmk[it & 1][3]; }
;                           Ot[it] = __builtin_amdgcn_mfma_f32_16x16x32_bf16(Vf[ks], __builtin_bit_cast(bf16x8, pw), Ot[it], 0, 0, 0);
;                           __builtin_amdgcn_sched_group_barrier(0x100, 1, 0); __builtin_amdgcn_sched_group_barrier(0x8, 1, 0); }); }
.LBB0_988:
	v_lshl_add_u64 v[152:153], s[64:65], 0, v[148:149]
	s_mov_b32 s12, 0x10800000
	v_add_co_u32_e32 v72, vcc, s12, v152
	v_mov_b32_e32 v192, v161
	v_mov_b32_e32 v74, v162
	v_lshl_add_u64 v[150:151], s[62:63], 0, v[148:149]
	v_addc_co_u32_e32 v73, vcc, 0, v153, vcc
	s_mov_b32 s12, 0x4a900000
	global_load_dwordx4 v[96:99], v[72:73], off offset:256
	v_add_co_u32_e32 v72, vcc, s12, v150
	s_mov_b32 s12, 0x10840000
	s_nop 0
	v_addc_co_u32_e32 v73, vcc, 0, v151, vcc
	global_load_dwordx4 v[100:103], v[72:73], off offset:256
	v_add_co_u32_e32 v72, vcc, s12, v152
	s_mov_b32 s12, 0x4a940000
	s_nop 0
	v_addc_co_u32_e32 v73, vcc, 0, v153, vcc
	global_load_dwordx4 v[104:107], v[72:73], off offset:256
	v_add_co_u32_e32 v72, vcc, s12, v150
	s_waitcnt vmcnt(14)
	ds_write_b128 v214, v[64:67] offset:16384
	v_addc_co_u32_e32 v73, vcc, 0, v151, vcc
	global_load_dwordx4 v[108:111], v[72:73], off offset:256
	v_lshlrev_b32_e32 v72, 3, v74
	s_waitcnt vmcnt(14)
	ds_write_b128 v214, v[68:71] offset:49152
	s_waitcnt vmcnt(13)
	ds_write_b128 v214, v[76:79] offset:24576
	s_waitcnt vmcnt(12)
	ds_write_b128 v214, v[84:87] offset:57344
	v_add_u32_e32 v64, v175, v168
	v_add_u32_e32 v65, v169, v168
	v_sub_u32_e32 v112, 0x7f, v72
	ds_read_b64_tr_b16 v[72:73], v64
	ds_read_b64_tr_b16 v[80:81], v64 offset:8192
	ds_read_b64_tr_b16 v[88:89], v64 offset:16384
	ds_read_b64_tr_b16 v[92:93], v64 offset:24576
	ds_read_b64_tr_b16 v[74:75], v65 offset:1024
	ds_read_b64_tr_b16 v[82:83], v65 offset:9216
	ds_read_b64_tr_b16 v[90:91], v65 offset:17408
	ds_read_b64_tr_b16 v[94:95], v65 offset:25600
	v_cvt_f32_i32_e32 v124, v112
	s_add_i32 s43, s44, 1
	s_cmp_lt_u32 s43, s73
	s_cselect_b64 s[22:23], -1, 0
	s_cmp_ge_u32 s43, s73
	v_add_u32_e32 v125, v170, v171
	ds_read_b128 v[64:67], v125
	ds_read_b128 v[76:79], v125 offset:4096
	v_add_u32_e32 v126, v170, v172
	v_add_u32_e32 v127, v170, v173
	v_add_u32_e32 v140, v170, v174
	s_waitcnt lgkmcnt(1)
	v_and_b32_e32 v64, v64, v205
	v_and_b32_e32 v65, v65, v206
	v_and_b32_e32 v66, v66, v207
	v_and_b32_e32 v67, v67, v208
	s_nop 1
	v_mfma_f32_16x16x32_bf16 v[68:71], v[72:75], v[64:67], 0
	ds_read_b128 v[84:87], v125 offset:8192
	s_waitcnt lgkmcnt(1)
	v_and_b32_e32 v64, v76, v209
	v_and_b32_e32 v65, v77, v210
	v_and_b32_e32 v66, v78, v211
	v_and_b32_e32 v67, v79, v212
	s_nop 1
	v_mfma_f32_16x16x32_bf16 v[64:67], v[72:75], v[64:67], 0
	ds_read_b128 v[76:79], v126 offset:8192
	s_waitcnt lgkmcnt(0)
	v_and_b32_e32 v76, v76, v205
	v_mfma_f32_16x16x32_bf16 v[84:87], v[72:75], v[84:87], 0
	ds_read_b128 v[112:115], v125 offset:12288
	v_and_b32_e32 v77, v77, v206
	v_and_b32_e32 v78, v78, v207
	v_and_b32_e32 v79, v79, v208
	s_nop 1
	v_mfma_f32_16x16x32_bf16 v[76:79], v[80:83], v[76:79], v[84:87]
	s_nop 2
	ds_read_b128 v[84:87], v126 offset:12288
	s_waitcnt lgkmcnt(1)
	v_mfma_f32_16x16x32_bf16 v[112:115], v[72:75], v[112:115], 0
	ds_read_b128 v[116:119], v125 offset:16384
	s_waitcnt lgkmcnt(1)
	v_and_b32_e32 v84, v84, v209
	v_and_b32_e32 v85, v85, v210
	v_and_b32_e32 v86, v86, v211
	v_and_b32_e32 v87, v87, v212
	s_nop 1
	v_mfma_f32_16x16x32_bf16 v[84:87], v[80:83], v[84:87], v[112:115]
	s_nop 2
	ds_read_b128 v[112:115], v126 offset:16384
	s_waitcnt lgkmcnt(1)
	v_mfma_f32_16x16x32_bf16 v[116:119], v[72:75], v[116:119], 0
	ds_read_b128 v[120:123], v127 offset:16384
	s_waitcnt lgkmcnt(0)
	v_and_b32_e32 v120, v120, v205
	v_mfma_f32_16x16x32_bf16 v[112:115], v[80:83], v[112:115], v[116:119]
	v_and_b32_e32 v121, v121, v206
	v_and_b32_e32 v122, v122, v207
	v_and_b32_e32 v123, v123, v208
	s_nop 0
	ds_read_b128 v[116:119], v125 offset:20480
	v_mfma_f32_16x16x32_bf16 v[128:131], v[88:91], v[120:123], v[112:115]
	s_nop 2
	ds_read_b128 v[112:115], v126 offset:20480
	s_waitcnt lgkmcnt(1)
	v_mfma_f32_16x16x32_bf16 v[116:119], v[72:75], v[116:119], 0
	ds_read_b128 v[120:123], v127 offset:20480
	s_waitcnt lgkmcnt(0)
	v_and_b32_e32 v120, v120, v209
	v_mfma_f32_16x16x32_bf16 v[112:115], v[80:83], v[112:115], v[116:119]
	v_and_b32_e32 v121, v121, v210
	v_and_b32_e32 v122, v122, v211
	v_and_b32_e32 v123, v123, v212
	s_nop 0
	ds_read_b128 v[116:119], v125 offset:24576
	v_mfma_f32_16x16x32_bf16 v[132:135], v[88:91], v[120:123], v[112:115]
	s_nop 2
	ds_read_b128 v[112:115], v126 offset:24576
	s_waitcnt lgkmcnt(1)
	v_mfma_f32_16x16x32_bf16 v[116:119], v[72:75], v[116:119], 0
	ds_read_b128 v[120:123], v127 offset:24576
	s_waitcnt lgkmcnt(1)
	v_mfma_f32_16x16x32_bf16 v[112:115], v[80:83], v[112:115], v[116:119]
	s_nop 4
	ds_read_b128 v[116:119], v140 offset:24576
	s_waitcnt lgkmcnt(1)
	v_mfma_f32_16x16x32_bf16 v[112:115], v[88:91], v[120:123], v[112:115]
	ds_read_b128 v[120:123], v125 offset:28672
	s_waitcnt lgkmcnt(1)
	v_and_b32_e32 v116, v116, v205
	v_and_b32_e32 v117, v117, v206
	v_and_b32_e32 v118, v118, v207
	v_and_b32_e32 v119, v119, v208
	s_nop 1
	v_mfma_f32_16x16x32_bf16 v[136:139], v[92:95], v[116:119], v[112:115]
	s_nop 2
	ds_read_b128 v[112:115], v126 offset:28672
	s_waitcnt lgkmcnt(1)
	v_mfma_f32_16x16x32_bf16 v[116:119], v[72:75], v[120:123], 0
	ds_read_b128 v[120:123], v127 offset:28672
	s_waitcnt lgkmcnt(1)
	v_mfma_f32_16x16x32_bf16 v[112:115], v[80:83], v[112:115], v[116:119]
	s_nop 4
	ds_read_b128 v[116:119], v140 offset:28672
	s_waitcnt lgkmcnt(1)
	v_mfma_f32_16x16x32_bf16 v[112:115], v[88:91], v[120:123], v[112:115]
	s_waitcnt lgkmcnt(0)
; __device__ __forceinline__ unsigned cvt_pk_bf16(float lo, float hi) { unsigned r; asm volatile("v_cvt_pk_bf16_f32 %0, %1, %2" : "=v"(r) : "v"(lo), "v"(hi)); return r; }
; __device__ __forceinline__ float bf_lo(unsigned w) { return __uint_as_float(w << 16); }
; __device__ __forceinline__ float bf_hi(unsigned w) { return __uint_as_float(w & 0xffff0000u); }
; #define SCAN_QREAD(b_, it_) do { _Pragma("unroll") for (int ks = 0; ks < 2; ++ks) { const int qo = ((p & 1) ? LQ1 : LQ0) + 16 * (it_) * QS; \
;                         const u32x2 lo = *(const volatile LAS u32x2*)(bQs[ks][0] + qo), hi = *(const volatile LAS u32x2*)(bQs[ks][1] + qo);     qf[b_][ks] = (u32x4){lo.x, lo.y, hi.x, hi.y}; } } while (0)
; __device__ __forceinline__ void scan_phase(const Frame& F, const bf16_t* Q, const bf16_t* K, const bf16_t* V, const bf16_t* PB, bf16_t* OF, bf16_t* OB, int half) {
;     ...
;                     { float fk = __builtin_amdgcn_exp2f(lg2 * (float)(dir ? 8 * quad_l : 127 - 8 * quad_l));
; #pragma unroll
;                       for (int ks = 0; ks < 4; ++ks) { u32x4 vw = __builtin_bit_cast(u32x4, Vf[ks]); float f = fk;
; #pragma unroll
;                         for (int e2 = 0; e2 < 4; ++e2) { const float f0 = f, f1 = f * gm1; f = f1 * gm1;
;                             vw[e2] = cvt_pk_bf16(bf_lo(vw[e2]) * f0, bf_hi(vw[e2]) * f1); }
;                         Vf[ks] = __builtin_bit_cast(bf16x8, vw); fk *= gm32; } }
;                 }
;                 __builtin_amdgcn_sched_barrier(0);
;                 {
;                     bf16x8 Rf[2];
; #pragma unroll
;                     for (int ks = 0; ks < 2; ++ks) { const f32x4 r0v = Rt[4 * p + 2 * ks], r1v = Rt[4 * p + 2 * ks + 1];
;                         const u32x4 wvv = {cvt_pk_bf16(r0v[0], r0v[1]), cvt_pk_bf16(r0v[2], r0v[3]), cvt_pk_bf16(r1v[0], r1v[1]), cvt_pk_bf16(r1v[2], r1v[3])};
;                         Rf[ks] = __builtin_bit_cast(bf16x8, wvv); }
;                     u32x4 qf[2][2];
;     ...
;                     SCAN_QREAD(0, 0);
; #pragma unroll
;                     for (int it = 0; it < 8; ++it) { if (it < 7) SCAN_QREAD((it + 1) & 1, it + 1);
; #pragma unroll
;                         for (int ks = 0; ks < 2; ++ks) Ot[it] = __builtin_amdgcn_mfma_f32_16x16x32_bf16(Rf[ks], __builtin_bit_cast(bf16x8, qf[it & 1][ks]), Ot[it], 0, 0, 0); }
	v_and_b32_e32 v116, v116, v209
	v_and_b32_e32 v117, v117, v210
	v_and_b32_e32 v118, v118, v211
	v_and_b32_e32 v119, v119, v212
	s_nop 1
	v_mfma_f32_16x16x32_bf16 v[140:143], v[92:95], v[116:119], v[112:115]
	s_nop 2
	v_mul_f32_e32 v112, s54, v124
	v_exp_f32_e32 v112, v112
	v_lshlrev_b32_e32 v113, 16, v72
	v_and_b32_e32 v72, 0xffff0000, v72
	v_lshlrev_b32_e32 v116, 16, v73
	v_mul_f32_e32 v114, s18, v112
	v_mul_f32_e32 v113, v112, v113
	v_mul_f32_e32 v115, s18, v114
	v_mul_f32_e32 v72, v114, v72
	v_cvt_pk_bf16_f32 v72, v113, v72
	v_mul_f32_e32 v113, s18, v115
	v_mul_f32_e32 v114, s18, v113
	v_and_b32_e32 v73, 0xffff0000, v73
	v_mul_f32_e32 v115, v115, v116
	v_mul_f32_e32 v73, v113, v73
	v_mul_f32_e32 v113, s18, v114
	v_lshlrev_b32_e32 v116, 16, v74
	v_and_b32_e32 v74, 0xffff0000, v74
	v_cvt_pk_bf16_f32 v73, v115, v73
	v_mul_f32_e32 v115, s18, v113
	v_mul_f32_e32 v114, v114, v116
	v_mul_f32_e32 v74, v113, v74
	v_cvt_pk_bf16_f32 v74, v114, v74
	v_mul_f32_e32 v113, s18, v115
	v_lshlrev_b32_e32 v114, 16, v75
	v_and_b32_e32 v75, 0xffff0000, v75
	v_mul_f32_e32 v112, s36, v112
	v_mul_f32_e32 v114, v115, v114
	v_mul_f32_e32 v75, v113, v75
	v_mul_f32_e32 v113, s18, v112
	v_cvt_pk_bf16_f32 v75, v114, v75
	v_mul_f32_e32 v114, s18, v113
	v_lshlrev_b32_e32 v115, 16, v80
	v_and_b32_e32 v80, 0xffff0000, v80
	v_mul_f32_e32 v115, v112, v115
	v_mul_f32_e32 v80, v113, v80
	v_mul_f32_e32 v113, s18, v114
	v_cvt_pk_bf16_f32 v80, v115, v80
	v_mul_f32_e32 v115, s18, v113
	v_lshlrev_b32_e32 v116, 16, v81
	v_and_b32_e32 v81, 0xffff0000, v81
	v_mul_f32_e32 v114, v114, v116
	v_mul_f32_e32 v81, v113, v81
	v_mul_f32_e32 v113, s18, v115
	v_lshlrev_b32_e32 v116, 16, v82
	v_and_b32_e32 v82, 0xffff0000, v82
	v_cvt_pk_bf16_f32 v81, v114, v81
	v_mul_f32_e32 v114, s18, v113
	v_mul_f32_e32 v115, v115, v116
	v_mul_f32_e32 v82, v113, v82
	v_cvt_pk_bf16_f32 v82, v115, v82
	v_mul_f32_e32 v113, s18, v114
	v_lshlrev_b32_e32 v115, 16, v83
	v_and_b32_e32 v83, 0xffff0000, v83
	v_mul_f32_e32 v112, s36, v112
	v_mul_f32_e32 v114, v114, v115
	v_mul_f32_e32 v83, v113, v83
	v_mul_f32_e32 v113, s18, v112
	v_cvt_pk_bf16_f32 v83, v114, v83
	v_mul_f32_e32 v114, s18, v113
	v_lshlrev_b32_e32 v115, 16, v88
	v_and_b32_e32 v88, 0xffff0000, v88
	v_mul_f32_e32 v115, v112, v115
	v_mul_f32_e32 v88, v113, v88
	v_mul_f32_e32 v113, s18, v114
	v_cvt_pk_bf16_f32 v88, v115, v88
	v_mul_f32_e32 v115, s18, v113
	v_lshlrev_b32_e32 v116, 16, v89
	v_and_b32_e32 v89, 0xffff0000, v89
	v_mul_f32_e32 v114, v114, v116
	v_mul_f32_e32 v89, v113, v89
	v_mul_f32_e32 v113, s18, v115
	v_lshlrev_b32_e32 v116, 16, v90
	v_and_b32_e32 v90, 0xffff0000, v90
	v_cvt_pk_bf16_f32 v89, v114, v89
	v_mul_f32_e32 v114, s18, v113
	v_mul_f32_e32 v115, v115, v116
	v_mul_f32_e32 v90, v113, v90
	v_cvt_pk_bf16_f32 v90, v115, v90
	v_mul_f32_e32 v113, s18, v114
	v_lshlrev_b32_e32 v115, 16, v91
	v_and_b32_e32 v91, 0xffff0000, v91
	v_mul_f32_e32 v112, s36, v112
	v_mul_f32_e32 v114, v114, v115
	v_mul_f32_e32 v91, v113, v91
	v_mul_f32_e32 v113, s18, v112
	v_lshlrev_b32_e32 v115, 16, v92
	v_and_b32_e32 v92, 0xffff0000, v92
	v_cvt_pk_bf16_f32 v91, v114, v91
	v_mul_f32_e32 v114, s18, v113
	v_mul_f32_e32 v112, v112, v115
	v_mul_f32_e32 v92, v113, v92
	v_cvt_pk_bf16_f32 v92, v112, v92
	v_mul_f32_e32 v112, s18, v114
	v_mul_f32_e32 v113, s18, v112
	v_lshlrev_b32_e32 v115, 16, v93
	v_and_b32_e32 v93, 0xffff0000, v93
	v_mul_f32_e32 v114, v114, v115
	v_mul_f32_e32 v93, v112, v93
	v_mul_f32_e32 v112, s18, v113
	v_lshlrev_b32_e32 v115, 16, v94
	v_and_b32_e32 v94, 0xffff0000, v94
	v_cvt_pk_bf16_f32 v93, v114, v93
	v_mul_f32_e32 v114, s18, v112
	v_mul_f32_e32 v113, v113, v115
	v_mul_f32_e32 v94, v112, v94
	v_cvt_pk_bf16_f32 v94, v113, v94
	v_mul_f32_e32 v112, s18, v114
	v_lshlrev_b32_e32 v113, 16, v95
	v_and_b32_e32 v95, 0xffff0000, v95
	v_mul_f32_e32 v113, v114, v113
	v_mul_f32_e32 v95, v112, v95
	v_cvt_pk_bf16_f32 v95, v113, v95
	v_add_u32_e32 v217, v163, v164
	v_add_u32_e32 v218, v163, v165
	v_cvt_pk_bf16_f32 v194, v44, v45
	v_cvt_pk_bf16_f32 v195, v46, v47
	v_cvt_pk_bf16_f32 v196, v40, v41
	v_cvt_pk_bf16_f32 v197, v42, v43
	v_cvt_pk_bf16_f32 v222, v36, v37
	v_cvt_pk_bf16_f32 v223, v38, v39
	v_cvt_pk_bf16_f32 v224, v32, v33
	v_cvt_pk_bf16_f32 v225, v34, v35
	ds_read_b64 v[112:113], v217
	ds_read_b64 v[114:115], v218
	v_add_u32_e32 v219, v163, v166
	v_add_u32_e32 v220, v163, v167
	ds_read_b64 v[116:117], v219
	ds_read_b64 v[118:119], v220
	ds_read_b64 v[120:121], v217 offset:2048
	ds_read_b64 v[122:123], v218 offset:2048
	ds_read_b64 v[124:125], v219 offset:2048
	ds_read_b64 v[126:127], v220 offset:2048
	s_waitcnt lgkmcnt(6)
	v_mfma_f32_16x16x32_bf16 v[68:71], v[194:197], v[112:115], v[68:71]
	s_waitcnt lgkmcnt(4)
	v_mfma_f32_16x16x32_bf16 v[112:115], v[222:225], v[116:119], v[68:71]
	s_nop 5
	ds_read_b64 v[68:69], v217 offset:4096
	ds_read_b64 v[70:71], v218 offset:4096
	ds_read_b64 v[226:227], v219 offset:4096
	ds_read_b64 v[228:229], v220 offset:4096
	s_waitcnt lgkmcnt(6)
	v_mfma_f32_16x16x32_bf16 v[64:67], v[194:197], v[120:123], v[64:67]
	s_waitcnt lgkmcnt(4)
	v_mfma_f32_16x16x32_bf16 v[116:119], v[222:225], v[124:127], v[64:67]
	s_nop 5
	ds_read_b64 v[64:65], v217 offset:6144
	ds_read_b64 v[66:67], v218 offset:6144
	ds_read_b64 v[124:125], v219 offset:6144
	ds_read_b64 v[126:127], v220 offset:6144
	s_waitcnt lgkmcnt(6)
	v_mfma_f32_16x16x32_bf16 v[68:71], v[194:197], v[68:71], v[76:79]
	s_waitcnt lgkmcnt(4)
	v_mfma_f32_16x16x32_bf16 v[120:123], v[222:225], v[226:229], v[68:71]
	s_nop 5
	ds_read_b64 v[68:69], v217 offset:8192
	ds_read_b64 v[70:71], v218 offset:8192
	ds_read_b64 v[76:77], v219 offset:8192
	ds_read_b64 v[78:79], v220 offset:8192
	s_waitcnt lgkmcnt(6)
; __device__ __forceinline__ bf16x8 pack8(s16x4 lo, s16x4 hi) { return (bf16x8){lo[0], lo[1], lo[2], lo[3], hi[0], hi[1], hi[2], hi[3]}; }
; #define SCAN_BAR() asm volatile("s_waitcnt lgkmcnt(0)\n\ts_barrier" ::: "memory")
; #define SCAN_WRITE_QK(par) do { _Pragma("unroll") for (int ii = 0; ii < 2; ++ii) { *(LAS u32x4*)(bSt + ((par) ? LQ1 : LQ0) + ii * 64 * QS) = rq[ii]; *(LAS u32x4*)(bSt + ((par) ? LK1 : LK0) + ii * 64 * QS) = rk[ii]; } } while (0)
; __device__ __forceinline__ void scan_phase(const Frame& F, const bf16_t* Q, const bf16_t* K, const bf16_t* V, const bf16_t* PB, bf16_t* OF, bf16_t* OB, int half) {
;     ...
;         unsigned pmk[2][4];
; #pragma unroll
;         for (int par = 0; par < 2; ++par) { int nk = 16 * par + l15 - 8 * quad + 1; nk = nk < 0 ? 0 : (nk > 8 ? 8 : nk);
; #pragma unroll
;             for (int d_ = 0; d_ < 4; ++d_) { const unsigned mf = ((2 * d_ < nk) ? 0xffffu : 0u) | ((2 * d_ + 1 < nk) ? 0xffff0000u : 0u); pmk[par][d_] = dir ? ~mf : mf; } }
;         { const int c0 = dir ? nchunk - 1 : 0; SCAN_DMA_VP(c0); SCAN_LOAD_QK(c0, 0); SCAN_WRITE_QK(0); SCAN_LOAD_QK(c0, 1); }
;         SCAN_BAR();
;         for (int s = 0; s < nchunk; ++s) {
;             const int c = dir ? nchunk - 1 - s : s, cn = dir ? nchunk - 2 - s : s + 1; const size_t r0 = rb + (size_t)c * 128; const bool more = s + 1 < nchunk;
;             f32x4 Ot[8]; bf16x8 Vf[4];
; #pragma unroll
;             for (int i = 0; i < 8; ++i) Ot[i] = (f32x4){0.f, 0.f, 0.f, 0.f};
;             int quad_l = quad, l15_l = l15; asm volatile("" : "+v"(quad_l), "+v"(l15_l));
; #pragma unroll
;             for (int p = 0; p < 4; ++p) {
;                 if (p < 3 || more) SCAN_WRITE_QK((p + 1) & 1);
;                 if (p == 1 && more) SCAN_DMA_VP(cn);
;                 if (p < 2) SCAN_LOAD_QK(c, p + 2); else if (more) SCAN_LOAD_QK(cn, p - 2);
;     ...
;                 { s16x4 kl[2][4], kh[2][4];
;     ...
;                 SCAN_KREAD(0, 0);
; #pragma unroll
;                 for (int mt = 0; mt < 4; ++mt) { if (mt < 3) SCAN_KREAD((mt + 1) & 1, mt + 1);
;                     f32x4 acc = Rt[4 * p + mt] * c1;
; #pragma unroll
;                     for (int ks = 0; ks < 4; ++ks) acc = __builtin_amdgcn_mfma_f32_16x16x32_bf16(pack8(kl[mt & 1][ks], kh[mt & 1][ks]), Vf[ks], acc, 0, 0, 0);
;                     Rt[4 * p + mt] = acc; }
	v_mfma_f32_16x16x32_bf16 v[64:67], v[194:197], v[64:67], v[84:87]
	s_waitcnt lgkmcnt(4)
	v_mfma_f32_16x16x32_bf16 v[124:127], v[222:225], v[124:127], v[64:67]
	s_nop 5
	ds_read_b64 v[64:65], v217 offset:10240
	ds_read_b64 v[66:67], v218 offset:10240
	ds_read_b64 v[84:85], v219 offset:10240
	ds_read_b64 v[86:87], v220 offset:10240
	s_waitcnt lgkmcnt(6)
	v_mfma_f32_16x16x32_bf16 v[68:71], v[194:197], v[68:71], v[128:131]
	s_waitcnt lgkmcnt(4)
	v_mfma_f32_16x16x32_bf16 v[128:131], v[222:225], v[76:79], v[68:71]
	s_nop 5
	ds_read_b64 v[68:69], v217 offset:12288
	ds_read_b64 v[70:71], v218 offset:12288
	ds_read_b64 v[76:77], v219 offset:12288
	ds_read_b64 v[78:79], v220 offset:12288
	s_waitcnt lgkmcnt(6)
	v_mfma_f32_16x16x32_bf16 v[64:67], v[194:197], v[64:67], v[132:135]
	s_waitcnt lgkmcnt(4)
	v_mfma_f32_16x16x32_bf16 v[132:135], v[222:225], v[84:87], v[64:67]
	s_nop 5
	ds_read_b64 v[64:65], v217 offset:14336
	ds_read_b64 v[66:67], v218 offset:14336
	ds_read_b64 v[84:85], v219 offset:14336
	ds_read_b64 v[86:87], v220 offset:14336
	s_waitcnt lgkmcnt(6)
	v_mfma_f32_16x16x32_bf16 v[68:71], v[194:197], v[68:71], v[136:139]
	s_waitcnt lgkmcnt(4)
	v_mfma_f32_16x16x32_bf16 v[136:139], v[222:225], v[76:79], v[68:71]
	s_waitcnt lgkmcnt(2)
	v_mfma_f32_16x16x32_bf16 v[64:67], v[194:197], v[64:67], v[140:143]
	s_waitcnt lgkmcnt(0)
	v_mfma_f32_16x16x32_bf16 v[140:143], v[222:225], v[84:87], v[64:67]
	v_add_u32_e32 v221, v182, v189
	v_add_u32_e32 v222, v182, v190
	s_nop 3
	ds_read_b64_tr_b16 v[64:65], v221 offset:32768
	ds_read_b64_tr_b16 v[66:67], v222 offset:33280
	ds_read_b64_tr_b16 v[68:69], v221 offset:36864
	ds_read_b64_tr_b16 v[70:71], v222 offset:37376
	v_mov_b32_e32 v145, v144
	ds_read_b64_tr_b16 v[76:77], v221 offset:40960
	ds_read_b64_tr_b16 v[78:79], v222 offset:41472
	v_add_u32_e32 v223, v182, v187
	v_add_u32_e32 v224, v182, v188
	v_pk_mul_f32 v[46:47], v[144:145], v[46:47]
	v_pk_mul_f32 v[44:45], v[146:147], v[44:45]
	ds_read_b64_tr_b16 v[84:85], v221 offset:45056
	ds_read_b64_tr_b16 v[86:87], v222 offset:45568
	ds_read_b64_tr_b16 v[194:195], v223 offset:32768
	ds_read_b64_tr_b16 v[196:197], v224 offset:33280
	ds_read_b64_tr_b16 v[228:229], v223 offset:36864
	ds_read_b64_tr_b16 v[230:231], v224 offset:37376
	ds_read_b64_tr_b16 v[232:233], v223 offset:40960
	ds_read_b64_tr_b16 v[234:235], v224 offset:41472
	ds_read_b64_tr_b16 v[236:237], v223 offset:45056
	ds_read_b64_tr_b16 v[238:239], v224 offset:45568
	s_waitcnt lgkmcnt(14)
	v_mfma_f32_16x16x32_bf16 v[44:47], v[64:67], v[72:75], v[44:47]
	v_add_u32_e32 v225, v182, v185
	v_add_u32_e32 v226, v182, v186
	v_pk_mul_f32 v[42:43], v[144:145], v[42:43]
	s_waitcnt lgkmcnt(12)
	v_mfma_f32_16x16x32_bf16 v[44:47], v[68:71], v[80:83], v[44:47]
	v_mul_f32_e64 v40, v146, v40
	v_mul_f32_e64 v41, v147, v41
	v_add_u32_e32 v227, v182, v183
	v_pk_mul_f32 v[38:39], v[144:145], v[38:39]
	s_waitcnt lgkmcnt(10)
	v_mfma_f32_16x16x32_bf16 v[44:47], v[76:79], v[88:91], v[44:47]
	v_mul_f32_e64 v36, v146, v36
	v_mul_f32_e64 v37, v147, v37
	v_pk_mul_f32 v[34:35], v[144:145], v[34:35]
	v_pk_mul_f32 v[32:33], v[146:147], v[32:33]
	s_waitcnt lgkmcnt(8)
	v_mfma_f32_16x16x32_bf16 v[44:47], v[84:87], v[92:95], v[44:47]
	ds_read_b64_tr_b16 v[64:65], v225 offset:32768
	ds_read_b64_tr_b16 v[66:67], v226 offset:33280
	ds_read_b64_tr_b16 v[68:69], v225 offset:36864
	ds_read_b64_tr_b16 v[70:71], v226 offset:37376
	ds_read_b64_tr_b16 v[76:77], v225 offset:40960
	ds_read_b64_tr_b16 v[78:79], v226 offset:41472
	ds_read_b64_tr_b16 v[84:85], v225 offset:45056
	ds_read_b64_tr_b16 v[86:87], v226 offset:45568
	s_waitcnt lgkmcnt(14)
	v_mfma_f32_16x16x32_bf16 v[40:43], v[194:197], v[72:75], v[40:43]
	s_waitcnt lgkmcnt(12)
	v_mfma_f32_16x16x32_bf16 v[40:43], v[228:231], v[80:83], v[40:43]
	v_add_u32_e32 v228, v182, v184
	s_waitcnt lgkmcnt(10)
	v_mfma_f32_16x16x32_bf16 v[40:43], v[232:235], v[88:91], v[40:43]
	s_waitcnt lgkmcnt(8)
	v_mfma_f32_16x16x32_bf16 v[40:43], v[236:239], v[92:95], v[40:43]
	ds_read_b64_tr_b16 v[194:195], v227 offset:32768
	ds_read_b64_tr_b16 v[196:197], v228 offset:33280
	ds_read_b64_tr_b16 v[230:231], v227 offset:36864
	ds_read_b64_tr_b16 v[232:233], v228 offset:37376
	ds_read_b64_tr_b16 v[234:235], v227 offset:40960
	ds_read_b64_tr_b16 v[236:237], v228 offset:41472
	ds_read_b64_tr_b16 v[238:239], v227 offset:45056
	ds_read_b64_tr_b16 v[240:241], v228 offset:45568
	s_waitcnt lgkmcnt(14)
	v_mfma_f32_16x16x32_bf16 v[36:39], v[64:67], v[72:75], v[36:39]
	s_waitcnt lgkmcnt(0)
	s_barrier
	s_waitcnt vmcnt(3)
	ds_write_b128 v214, v[96:99]
	s_waitcnt vmcnt(2)
	ds_write_b128 v214, v[100:103] offset:32768
	s_waitcnt lgkmcnt(14)
	v_mfma_f32_16x16x32_bf16 v[36:39], v[68:71], v[80:83], v[36:39]
	s_waitcnt vmcnt(1)
	ds_write_b128 v214, v[104:107] offset:8192
	s_waitcnt vmcnt(0)
	ds_write_b128 v214, v[108:111] offset:40960
	s_waitcnt lgkmcnt(14)
	v_mfma_f32_16x16x32_bf16 v[36:39], v[76:79], v[88:91], v[36:39]
	s_waitcnt lgkmcnt(12)
	v_mfma_f32_16x16x32_bf16 v[36:39], v[84:87], v[92:95], v[36:39]
	s_waitcnt lgkmcnt(10)
	v_mfma_f32_16x16x32_bf16 v[32:35], v[194:197], v[72:75], v[32:35]
	s_waitcnt lgkmcnt(8)
	v_mfma_f32_16x16x32_bf16 v[32:35], v[230:233], v[80:83], v[32:35]
	s_waitcnt lgkmcnt(6)
	v_mfma_f32_16x16x32_bf16 v[32:35], v[234:237], v[88:91], v[32:35]
	s_waitcnt lgkmcnt(4)
	v_mfma_f32_16x16x32_bf16 v[32:35], v[238:241], v[92:95], v[32:35]
	v_add_co_u32_e32 v64, vcc, 0x10800000, v152
	s_nop 1
	v_addc_co_u32_e32 v65, vcc, 0, v153, vcc
	v_add_co_u32_e32 v68, vcc, 0x4a900000, v150
	global_load_dwordx4 v[64:67], v[64:65], off offset:384
	s_nop 0
	v_addc_co_u32_e32 v69, vcc, 0, v151, vcc
	v_add_co_u32_e32 v76, vcc, 0x10840000, v152
	global_load_dwordx4 v[68:71], v[68:69], off offset:384
	s_nop 0
	v_addc_co_u32_e32 v77, vcc, 0, v153, vcc
	v_add_co_u32_e32 v84, vcc, 0x4a940000, v150
	global_load_dwordx4 v[76:79], v[76:77], off offset:384
	s_nop 0
	v_addc_co_u32_e32 v85, vcc, 0, v151, vcc
	global_load_dwordx4 v[84:87], v[84:85], off offset:384
	s_cbranch_scc1 .LBB0_990
	s_add_i32 s12, s40, s44
	s_ashr_i32 s13, s12, 31
	s_lshl_b64 s[12:13], s[12:13], 18
	s_add_u32 s12, s38, s12
	s_mov_b32 s34, m0
	s_mov_b32 m0, s74
	s_nop 0
	global_load_lds_dwordx4 v154, s[30:31]
	s_mov_b32 m0, s34
	s_addc_u32 s13, s39, s13
	s_mov_b32 s34, m0
	s_mov_b32 m0, s75
	s_nop 0
	global_load_lds_dwordx4 v155, s[12:13]
	s_mov_b32 m0, s34
	s_nop 0
	s_mov_b32 s34, m0
	s_mov_b32 m0, s79
	s_nop 0
	global_load_lds_dwordx4 v156, s[30:31]
	s_mov_b32 m0, s34
	s_nop 0
	s_mov_b32 s34, m0
	s_mov_b32 m0, s80
	s_nop 0
	global_load_lds_dwordx4 v157, s[12:13]
	s_mov_b32 m0, s34
	s_nop 0
	s_mov_b32 s34, m0
	s_mov_b32 m0, s81
	s_nop 0
	global_load_lds_dwordx4 v158, s[30:31]
	s_mov_b32 m0, s34
	s_nop 0
	s_mov_b32 s34, m0
	s_mov_b32 m0, s82
	s_nop 0
	global_load_lds_dwordx4 v159, s[12:13]
	s_mov_b32 m0, s34
	s_nop 0
	s_mov_b32 s34, m0
	s_mov_b32 m0, s83
	s_nop 0
	global_load_lds_dwordx4 v215, s[30:31]
	s_mov_b32 m0, s34
	s_nop 0
	s_mov_b32 s34, m0
	s_mov_b32 m0, s84
	s_nop 0
	global_load_lds_dwordx4 v216, s[12:13]
	s_mov_b32 m0, s34
; __device__ __forceinline__ void scan_phase(const Frame& F, const bf16_t* Q, const bf16_t* K, const bf16_t* V, const bf16_t* PB, bf16_t* OF, bf16_t* OB, int half) {
;     ...
;                 {
;                     bf16x8 Rf[2];
; #pragma unroll
;                     for (int ks = 0; ks < 2; ++ks) { const f32x4 r0v = Rt[4 * p + 2 * ks], r1v = Rt[4 * p + 2 * ks + 1];
;                         const u32x4 wvv = {cvt_pk_bf16(r0v[0], r0v[1]), cvt_pk_bf16(r0v[2], r0v[3]), cvt_pk_bf16(r1v[0], r1v[1]), cvt_pk_bf16(r1v[2], r1v[3])};
;                         Rf[ks] = __builtin_bit_cast(bf16x8, wvv); }
;                     u32x4 qf[2][2];
;     ...
;                     SCAN_QREAD(0, 0);
; #pragma unroll
;                     for (int it = 0; it < 8; ++it) { if (it < 7) SCAN_QREAD((it + 1) & 1, it + 1);
; #pragma unroll
;                         for (int ks = 0; ks < 2; ++ks) Ot[it] = __builtin_amdgcn_mfma_f32_16x16x32_bf16(Rf[ks], __builtin_bit_cast(bf16x8, qf[it & 1][ks]), Ot[it], 0, 0, 0); }
;     ...
;                     __builtin_amdgcn_sched_group_barrier(0x100, 4, 0);
;                     __builtin_amdgcn_sched_group_barrier(0x100, 4, 0); __builtin_amdgcn_sched_group_barrier(0x8, 2, 0);
;                     __builtin_amdgcn_sched_group_barrier(0x100, 4, 0); __builtin_amdgcn_sched_group_barrier(0x8, 2, 0);
;                     __builtin_amdgcn_sched_group_barrier(0x100, 4, 0); __builtin_amdgcn_sched_group_barrier(0x8, 2, 0);
;                     __builtin_amdgcn_sched_group_barrier(0x100, 4, 0); __builtin_amdgcn_sched_group_barrier(0x8, 2, 0);
;                     __builtin_amdgcn_sched_group_barrier(0x100, 4, 0); __builtin_amdgcn_sched_group_barrier(0x8, 2, 0);
;                     __builtin_amdgcn_sched_group_barrier(0x100, 4, 0); __builtin_amdgcn_sched_group_barrier(0x8, 2, 0);
;                     __builtin_amdgcn_sched_group_barrier(0x100, 4, 0); __builtin_amdgcn_sched_group_barrier(0x8, 2, 0);
;                     __builtin_amdgcn_sched_group_barrier(0x8, 2, 0);
;                 }
;                 __builtin_amdgcn_sched_barrier(0);
;                 { s16x4 kl[2][4], kh[2][4];
;     ...
;                 SCAN_KREAD(0, 0);
; #pragma unroll
;                 for (int mt = 0; mt < 4; ++mt) { if (mt < 3) SCAN_KREAD((mt + 1) & 1, mt + 1);
;                     f32x4 acc = Rt[4 * p + mt] * c1;
; #pragma unroll
.LBB0_990:
	v_cvt_pk_bf16_f32 v194, v28, v29
	v_cvt_pk_bf16_f32 v195, v30, v31
	v_cvt_pk_bf16_f32 v196, v20, v21
	v_cvt_pk_bf16_f32 v197, v22, v23
	v_cvt_pk_bf16_f32 v230, v16, v17
	v_cvt_pk_bf16_f32 v231, v18, v19
	v_cvt_pk_bf16_f32 v232, v24, v25
	v_cvt_pk_bf16_f32 v233, v26, v27
	ds_read_b64 v[96:97], v217 offset:16384
	ds_read_b64 v[98:99], v218 offset:16384
	ds_read_b64 v[100:101], v219 offset:16384
	ds_read_b64 v[102:103], v220 offset:16384
	ds_read_b64 v[104:105], v217 offset:18432
	ds_read_b64 v[106:107], v218 offset:18432
	ds_read_b64 v[108:109], v219 offset:18432
	ds_read_b64 v[110:111], v220 offset:18432
	s_waitcnt lgkmcnt(6)
	v_mfma_f32_16x16x32_bf16 v[96:99], v[194:197], v[96:99], v[112:115]
	s_waitcnt lgkmcnt(4)
	v_mfma_f32_16x16x32_bf16 v[96:99], v[230:233], v[100:103], v[96:99]
	s_nop 0
	ds_read_b64 v[112:113], v217 offset:20480
	ds_read_b64 v[114:115], v218 offset:20480
	ds_read_b64 v[234:235], v219 offset:20480
	ds_read_b64 v[236:237], v220 offset:20480
	s_waitcnt lgkmcnt(6)
	v_mfma_f32_16x16x32_bf16 v[100:103], v[194:197], v[104:107], v[116:119]
	s_waitcnt lgkmcnt(4)
	v_mfma_f32_16x16x32_bf16 v[100:103], v[230:233], v[108:111], v[100:103]
	ds_read_b64 v[108:109], v217 offset:22528
	ds_read_b64 v[110:111], v218 offset:22528
	ds_read_b64 v[116:117], v219 offset:22528
	ds_read_b64 v[118:119], v220 offset:22528
	s_waitcnt lgkmcnt(6)
	v_mfma_f32_16x16x32_bf16 v[104:107], v[194:197], v[112:115], v[120:123]
	s_waitcnt lgkmcnt(4)
	v_mfma_f32_16x16x32_bf16 v[104:107], v[230:233], v[234:237], v[104:107]
	ds_read_b64 v[112:113], v217 offset:24576
	ds_read_b64 v[114:115], v218 offset:24576
	ds_read_b64 v[120:121], v219 offset:24576
	ds_read_b64 v[122:123], v220 offset:24576
	s_waitcnt lgkmcnt(6)
	v_mfma_f32_16x16x32_bf16 v[108:111], v[194:197], v[108:111], v[124:127]
	s_waitcnt lgkmcnt(4)
	v_mfma_f32_16x16x32_bf16 v[108:111], v[230:233], v[116:119], v[108:111]
	ds_read_b64 v[116:117], v217 offset:26624
	ds_read_b64 v[118:119], v218 offset:26624
	ds_read_b64 v[124:125], v219 offset:26624
	ds_read_b64 v[126:127], v220 offset:26624
	s_waitcnt lgkmcnt(6)
	v_mfma_f32_16x16x32_bf16 v[112:115], v[194:197], v[112:115], v[128:131]
	s_waitcnt lgkmcnt(4)
	v_mfma_f32_16x16x32_bf16 v[112:115], v[230:233], v[120:123], v[112:115]
	ds_read_b64 v[120:121], v217 offset:28672
	ds_read_b64 v[122:123], v218 offset:28672
	ds_read_b64 v[128:129], v219 offset:28672
	ds_read_b64 v[130:131], v220 offset:28672
	s_waitcnt lgkmcnt(6)
	v_mfma_f32_16x16x32_bf16 v[116:119], v[194:197], v[116:119], v[132:135]
	s_waitcnt lgkmcnt(4)
	v_mfma_f32_16x16x32_bf16 v[116:119], v[230:233], v[124:127], v[116:119]
	ds_read_b64 v[124:125], v217 offset:30720
	ds_read_b64 v[126:127], v218 offset:30720
	ds_read_b64 v[132:133], v219 offset:30720
	ds_read_b64 v[134:135], v220 offset:30720
	s_waitcnt lgkmcnt(6)
	v_mfma_f32_16x16x32_bf16 v[120:123], v[194:197], v[120:123], v[136:139]
	s_waitcnt lgkmcnt(4)
	v_mfma_f32_16x16x32_bf16 v[120:123], v[230:233], v[128:131], v[120:123]
	s_waitcnt lgkmcnt(2)
	v_mfma_f32_16x16x32_bf16 v[124:127], v[194:197], v[124:127], v[140:143]
	s_waitcnt lgkmcnt(0)
	v_mfma_f32_16x16x32_bf16 v[124:127], v[230:233], v[132:135], v[124:127]
	ds_read_b64_tr_b16 v[128:129], v221 offset:49152
	ds_read_b64_tr_b16 v[130:131], v222 offset:49664
	ds_read_b64_tr_b16 v[132:133], v221 offset:53248
	ds_read_b64_tr_b16 v[134:135], v222 offset:53760
	ds_read_b64_tr_b16 v[136:137], v221 offset:57344
	ds_read_b64_tr_b16 v[138:139], v222 offset:57856
	v_pk_mul_f32 v[30:31], v[144:145], v[30:31]
	v_pk_mul_f32 v[28:29], v[146:147], v[28:29]
	ds_read_b64_tr_b16 v[140:141], v221 offset:61440
	ds_read_b64_tr_b16 v[142:143], v222 offset:61952
	ds_read_b64_tr_b16 v[194:195], v223 offset:49152
	ds_read_b64_tr_b16 v[196:197], v224 offset:49664
	ds_read_b64_tr_b16 v[230:231], v223 offset:53248
	ds_read_b64_tr_b16 v[232:233], v224 offset:53760
	ds_read_b64_tr_b16 v[234:235], v223 offset:57344
	ds_read_b64_tr_b16 v[236:237], v224 offset:57856
	ds_read_b64_tr_b16 v[238:239], v223 offset:61440
	ds_read_b64_tr_b16 v[240:241], v224 offset:61952
	s_waitcnt lgkmcnt(14)
	v_mfma_f32_16x16x32_bf16 v[28:31], v[128:131], v[72:75], v[28:31]
	v_mul_f32_e64 v22, v144, v22
	v_mul_f32_e64 v23, v145, v23
	v_pk_mul_f32 v[20:21], v[146:147], v[20:21]
	v_pk_mul_f32 v[18:19], v[144:145], v[18:19]
	s_waitcnt lgkmcnt(12)
	v_mfma_f32_16x16x32_bf16 v[28:31], v[132:135], v[80:83], v[28:31]
	v_mul_f32_e64 v16, v146, v16
	v_mul_f32_e64 v17, v147, v17
	v_pk_mul_f32 v[26:27], v[144:145], v[26:27]
	v_pk_mul_f32 v[24:25], v[146:147], v[24:25]
	s_waitcnt lgkmcnt(10)
	v_mfma_f32_16x16x32_bf16 v[28:31], v[136:139], v[88:91], v[28:31]
	s_andn2_b64 vcc, exec, s[22:23]
	s_waitcnt lgkmcnt(8)
	v_mfma_f32_16x16x32_bf16 v[28:31], v[140:143], v[92:95], v[28:31]
	ds_read_b64_tr_b16 v[128:129], v225 offset:49152
	ds_read_b64_tr_b16 v[130:131], v226 offset:49664
	ds_read_b64_tr_b16 v[132:133], v225 offset:53248
	ds_read_b64_tr_b16 v[134:135], v226 offset:53760
	ds_read_b64_tr_b16 v[136:137], v225 offset:57344
	ds_read_b64_tr_b16 v[138:139], v226 offset:57856
	ds_read_b64_tr_b16 v[140:141], v225 offset:61440
	ds_read_b64_tr_b16 v[142:143], v226 offset:61952
	s_waitcnt lgkmcnt(14)
	v_mfma_f32_16x16x32_bf16 v[20:23], v[194:197], v[72:75], v[20:23]
	s_waitcnt lgkmcnt(12)
	v_mfma_f32_16x16x32_bf16 v[20:23], v[230:233], v[80:83], v[20:23]
	s_waitcnt lgkmcnt(10)
	v_mfma_f32_16x16x32_bf16 v[20:23], v[234:237], v[88:91], v[20:23]
	s_waitcnt lgkmcnt(8)
	v_mfma_f32_16x16x32_bf16 v[20:23], v[238:241], v[92:95], v[20:23]
	ds_read_b64_tr_b16 v[194:195], v227 offset:49152
	ds_read_b64_tr_b16 v[196:197], v228 offset:49664
	ds_read_b64_tr_b16 v[230:231], v227 offset:53248
	ds_read_b64_tr_b16 v[232:233], v228 offset:53760
	ds_read_b64_tr_b16 v[234:235], v227 offset:57344
	ds_read_b64_tr_b16 v[236:237], v228 offset:57856
	ds_read_b64_tr_b16 v[238:239], v227 offset:61440
	ds_read_b64_tr_b16 v[240:241], v228 offset:61952
	s_waitcnt lgkmcnt(14)
	v_mfma_f32_16x16x32_bf16 v[16:19], v[128:131], v[72:75], v[16:19]
	s_waitcnt lgkmcnt(0)
	s_barrier
	v_cndmask_b32_e64 v128, 0, 1, s[22:23]
	v_cmp_ne_u32_e64 s[34:35], 1, v128
	s_waitcnt lgkmcnt(12)
	v_mfma_f32_16x16x32_bf16 v[16:19], v[132:135], v[80:83], v[16:19]
	s_cbranch_vccnz .Lscan1_nodma
	s_waitcnt vmcnt(8)
	s_branch .Lscan1_wdone

; __device__ __forceinline__ bf16x8 pack8(s16x4 lo, s16x4 hi) { return (bf16x8){lo[0], lo[1], lo[2], lo[3], hi[0], hi[1], hi[2], hi[3]}; }
; #define SCAN_LOAD_QK(cc, pq) do { const size_t u0_ = (rb + (size_t)(cc) * 128) * 2048 + head * 256 + (pq) * 64;     \
;             _Pragma("unroll") for (int ii = 0; ii < 2; ++ii) { rq[ii] = *(const GAS u32x4*)(Q + u0_ + (size_t)ii * 64 * 2048 + lqk_l); rk[ii] = *(const GAS u32x4*)(K + u0_ + (size_t)ii * 64 * 2048 + lqk_l); } } while (0)
; #define SCAN_WRITE_QK(par) do { _Pragma("unroll") for (int ii = 0; ii < 2; ++ii) { *(LAS u32x4*)(bSt + ((par) ? LQ1 : LQ0) + ii * 64 * QS) = rq[ii]; *(LAS u32x4*)(bSt + ((par) ? LK1 : LK0) + ii * 64 * QS) = rk[ii]; } } while (0)
; #define SCAN_KREAD(b_, mt_) do { _Pragma("unroll") for (int ks = 0; ks < 4; ++ks) { const int ko = ((p & 1) ? LK1 : LK0) + 32 * ks * QS; kl[b_][ks] = tr_read(bKlo[mt_] + ko); kh[b_][ks] = tr_read(bKhi[mt_] + ko); } } while (0)
; __device__ __forceinline__ void scan_phase(const Frame& F, const bf16_t* Q, const bf16_t* K, const bf16_t* V, const bf16_t* PB, bf16_t* OF, bf16_t* OB, int half) {
;     ...
;                 if (p < 3 || more) SCAN_WRITE_QK((p + 1) & 1);
;                 if (p == 1 && more) SCAN_DMA_VP(cn);
;                 if (p < 2) SCAN_LOAD_QK(c, p + 2); else if (more) SCAN_LOAD_QK(cn, p - 2);
;     ...
;                 { s16x4 kl[2][4], kh[2][4];
;     ...
;                 SCAN_KREAD(0, 0);
; #pragma unroll
;                 for (int mt = 0; mt < 4; ++mt) { if (mt < 3) SCAN_KREAD((mt + 1) & 1, mt + 1);
;                     f32x4 acc = Rt[4 * p + mt] * c1;
; #pragma unroll
;                     for (int ks = 0; ks < 4; ++ks) acc = __builtin_amdgcn_mfma_f32_16x16x32_bf16(pack8(kl[mt & 1][ks], kh[mt & 1][ks]), Vf[ks], acc, 0, 0, 0);
;                     Rt[4 * p + mt] = acc; }
.Lscan1_wdone:
	ds_write_b128 v214, v[64:67] offset:16384
	ds_write_b128 v214, v[68:71] offset:49152
	ds_write_b128 v214, v[76:79] offset:24576
	s_waitcnt lgkmcnt(13)
	v_mfma_f32_16x16x32_bf16 v[16:19], v[136:139], v[88:91], v[16:19]
	ds_write_b128 v214, v[84:87] offset:57344
	s_waitcnt lgkmcnt(12)
	v_mfma_f32_16x16x32_bf16 v[16:19], v[140:143], v[92:95], v[16:19]
	s_waitcnt lgkmcnt(10)
	v_mfma_f32_16x16x32_bf16 v[24:27], v[194:197], v[72:75], v[24:27]
	s_waitcnt lgkmcnt(8)
	v_mfma_f32_16x16x32_bf16 v[24:27], v[230:233], v[80:83], v[24:27]
	s_waitcnt lgkmcnt(6)
	v_mfma_f32_16x16x32_bf16 v[24:27], v[234:237], v[88:91], v[24:27]
	s_waitcnt lgkmcnt(4)
	v_mfma_f32_16x16x32_bf16 v[24:27], v[238:241], v[92:95], v[24:27]
	s_cbranch_vccnz .LBB0_992
	v_add_co_u32_e32 v64, vcc, 0x10880000, v152
	s_nop 1
	v_addc_co_u32_e32 v65, vcc, 0, v153, vcc
	v_add_co_u32_e32 v68, vcc, 0x4a980000, v150
	global_load_dwordx4 v[64:67], v[64:65], off
	s_nop 0
	v_addc_co_u32_e32 v69, vcc, 0, v151, vcc
	v_add_co_u32_e32 v76, vcc, 0x108c0000, v152
	global_load_dwordx4 v[68:71], v[68:69], off
	s_nop 0
	v_addc_co_u32_e32 v77, vcc, 0, v153, vcc
	v_add_co_u32_e32 v84, vcc, 0x4a9c0000, v150
	global_load_dwordx4 v[76:79], v[76:77], off
	s_nop 0
	v_addc_co_u32_e32 v85, vcc, 0, v151, vcc
	global_load_dwordx4 v[84:87], v[84:85], off

; __device__ __forceinline__ void cvt_job(const Frame& F, const float* W, int K, int Nsrc, bf16_t* dst, int nrows, int mode, float scale, const float* gain = nullptr) {
;     ...
;     for (int it = F.gw; it < nitems; it += F.NGW) {
;         const int kb = it / nblk, nb = it % nblk, k0 = 64 * kb, n0 = 32 * nb;
;         const int nsrc = map_col(mode, n0 + (lane & 31));
; #pragma unroll 8
;         for (int i = 0; i < 32; ++i) { const int kk = 2 * i + (lane >> 5); scr[kk * 33 + (lane & 31)] = (mode == MAP_ZERO) ? 0.f : W[(size_t)(k0 + kk) * Nsrc + nsrc] * (gain ? scale * gain[k0 + kk] : scale); }
.LBB0_1729:
	s_lshl_b32 s49, s36, 1
	s_lshl_b32 s48, s35, 1
	v_or_b32_e32 v18, s49, v0
	v_or_b32_e32 v13, s48, v1
	v_add_u32_e32 v16, s30, v18
	v_add_u32_e32 v14, s31, v13
	v_ashrrev_i32_e32 v17, 31, v16
	v_ashrrev_i32_e32 v15, 31, v14
	v_lshlrev_b64 v[16:17], 13, v[16:17]
	v_lshlrev_b64 v[14:15], 13, v[14:15]
	v_lshl_add_u64 v[16:17], v[6:7], 0, v[16:17]
	v_lshl_add_u64 v[14:15], v[6:7], 0, v[14:15]
	global_load_dword v64, v[16:17], off
	global_load_dword v65, v[14:15], off
	v_mad_u64_u32 v[14:15], s[12:13], v18, s21, v[2:3]
	v_mad_u64_u32 v[16:17], s[12:13], v13, s21, v[2:3]
	s_add_i32 s13, s49, 4
	s_add_i32 s12, s48, 4
	v_or_b32_e32 v18, s13, v0
	v_or_b32_e32 v13, s12, v1
	s_add_i32 s36, s36, 16
	s_add_i32 s35, s35, 16
	s_add_i32 s37, s37, -16
	v_mov_b32_e32 v80, v14
	v_mov_b32_e32 v81, v16
	v_add_u32_e32 v16, s30, v18
	v_add_u32_e32 v14, s31, v13
	v_ashrrev_i32_e32 v17, 31, v16
	v_ashrrev_i32_e32 v15, 31, v14
	v_lshlrev_b64 v[16:17], 13, v[16:17]
	v_lshlrev_b64 v[14:15], 13, v[14:15]
	v_lshl_add_u64 v[16:17], v[6:7], 0, v[16:17]
	v_lshl_add_u64 v[14:15], v[6:7], 0, v[14:15]
	global_load_dword v66, v[16:17], off
	global_load_dword v67, v[14:15], off
	v_mad_u64_u32 v[14:15], s[12:13], v18, s21, v[2:3]
	v_mad_u64_u32 v[16:17], s[12:13], v13, s21, v[2:3]
	s_add_i32 s13, s49, 8
	s_add_i32 s12, s48, 8
	v_or_b32_e32 v18, s13, v0
	v_or_b32_e32 v13, s12, v1
	v_mov_b32_e32 v82, v14
	v_mov_b32_e32 v83, v16
	v_add_u32_e32 v16, s30, v18
	v_add_u32_e32 v14, s31, v13
	v_ashrrev_i32_e32 v17, 31, v16
	v_ashrrev_i32_e32 v15, 31, v14
	v_lshlrev_b64 v[16:17], 13, v[16:17]
	v_lshlrev_b64 v[14:15], 13, v[14:15]
	v_lshl_add_u64 v[16:17], v[6:7], 0, v[16:17]
	v_lshl_add_u64 v[14:15], v[6:7], 0, v[14:15]
	global_load_dword v68, v[16:17], off
	global_load_dword v69, v[14:15], off
	v_mad_u64_u32 v[14:15], s[12:13], v18, s21, v[2:3]
	v_mad_u64_u32 v[16:17], s[12:13], v13, s21, v[2:3]
	s_add_i32 s13, s49, 12
	s_add_i32 s12, s48, 12
	v_or_b32_e32 v18, s13, v0
	v_or_b32_e32 v13, s12, v1
	v_mov_b32_e32 v84, v14
	v_mov_b32_e32 v85, v16
	v_add_u32_e32 v16, s30, v18
	v_add_u32_e32 v14, s31, v13
	v_ashrrev_i32_e32 v17, 31, v16
	v_ashrrev_i32_e32 v15, 31, v14
	v_lshlrev_b64 v[16:17], 13, v[16:17]
	v_lshlrev_b64 v[14:15], 13, v[14:15]
	v_lshl_add_u64 v[16:17], v[6:7], 0, v[16:17]
	v_lshl_add_u64 v[14:15], v[6:7], 0, v[14:15]
	global_load_dword v70, v[16:17], off
	global_load_dword v71, v[14:15], off
	v_mad_u64_u32 v[14:15], s[12:13], v18, s21, v[2:3]
	v_mad_u64_u32 v[16:17], s[12:13], v13, s21, v[2:3]
	s_add_i32 s13, s49, 16
	s_add_i32 s12, s48, 16
	v_or_b32_e32 v18, s13, v0
	v_or_b32_e32 v13, s12, v1
	v_mov_b32_e32 v86, v14
	v_mov_b32_e32 v87, v16
	v_add_u32_e32 v16, s30, v18
	v_add_u32_e32 v14, s31, v13
	v_ashrrev_i32_e32 v17, 31, v16
	v_ashrrev_i32_e32 v15, 31, v14
	v_lshlrev_b64 v[16:17], 13, v[16:17]
	v_lshlrev_b64 v[14:15], 13, v[14:15]
	v_lshl_add_u64 v[16:17], v[6:7], 0, v[16:17]
	v_lshl_add_u64 v[14:15], v[6:7], 0, v[14:15]
	global_load_dword v72, v[16:17], off
	global_load_dword v73, v[14:15], off
	v_mad_u64_u32 v[14:15], s[12:13], v18, s21, v[2:3]
	v_mad_u64_u32 v[16:17], s[12:13], v13, s21, v[2:3]
	s_add_i32 s13, s49, 20
	s_add_i32 s12, s48, 20
	v_or_b32_e32 v18, s13, v0
	v_or_b32_e32 v13, s12, v1
	v_mov_b32_e32 v88, v14
	v_mov_b32_e32 v89, v16
	v_add_u32_e32 v16, s30, v18
	v_add_u32_e32 v14, s31, v13
	v_ashrrev_i32_e32 v17, 31, v16
	v_ashrrev_i32_e32 v15, 31, v14
	v_lshlrev_b64 v[16:17], 13, v[16:17]
	v_lshlrev_b64 v[14:15], 13, v[14:15]
	v_lshl_add_u64 v[16:17], v[6:7], 0, v[16:17]
	v_lshl_add_u64 v[14:15], v[6:7], 0, v[14:15]
	global_load_dword v74, v[16:17], off
	global_load_dword v75, v[14:15], off
	v_mad_u64_u32 v[14:15], s[12:13], v18, s21, v[2:3]
	v_mad_u64_u32 v[16:17], s[12:13], v13, s21, v[2:3]
	s_add_i32 s13, s49, 24
	s_add_i32 s12, s48, 24
	v_or_b32_e32 v18, s13, v0
	v_or_b32_e32 v13, s12, v1
	s_add_i32 s49, s49, 28
	s_add_i32 s48, s48, 28
	s_cmp_lg_u32 s37, 0
	v_mov_b32_e32 v90, v14
	v_mov_b32_e32 v91, v16
	v_add_u32_e32 v16, s30, v18
	v_add_u32_e32 v14, s31, v13
	v_ashrrev_i32_e32 v17, 31, v16
	v_ashrrev_i32_e32 v15, 31, v14
	v_lshlrev_b64 v[16:17], 13, v[16:17]
	v_lshlrev_b64 v[14:15], 13, v[14:15]
	v_lshl_add_u64 v[16:17], v[6:7], 0, v[16:17]
	v_lshl_add_u64 v[14:15], v[6:7], 0, v[14:15]
	global_load_dword v76, v[16:17], off
	global_load_dword v77, v[14:15], off
	v_mad_u64_u32 v[14:15], s[12:13], v18, s21, v[2:3]
	v_mad_u64_u32 v[16:17], s[12:13], v13, s21, v[2:3]
	v_or_b32_e32 v18, s49, v0
	v_or_b32_e32 v13, s48, v1
	v_mov_b32_e32 v92, v14
	v_mov_b32_e32 v93, v16
	v_add_u32_e32 v16, s30, v18
	v_add_u32_e32 v14, s31, v13
	v_ashrrev_i32_e32 v17, 31, v16
	v_ashrrev_i32_e32 v15, 31, v14
	v_lshlrev_b64 v[16:17], 13, v[16:17]
	v_lshlrev_b64 v[14:15], 13, v[14:15]
	v_lshl_add_u64 v[16:17], v[6:7], 0, v[16:17]
	v_lshl_add_u64 v[14:15], v[6:7], 0, v[14:15]
	global_load_dword v78, v[16:17], off
	global_load_dword v79, v[14:15], off
	v_mad_u64_u32 v[14:15], s[12:13], v18, s21, v[2:3]
	v_mad_u64_u32 v[16:17], s[12:13], v13, s21, v[2:3]
	v_mov_b32_e32 v94, v14
	v_mov_b32_e32 v95, v16
	s_waitcnt vmcnt(15)
	ds_write_b32 v80, v64
	s_waitcnt vmcnt(14)
	ds_write_b32 v81, v65
	s_waitcnt vmcnt(13)
	ds_write_b32 v82, v66
	s_waitcnt vmcnt(12)
	ds_write_b32 v83, v67
	s_waitcnt vmcnt(11)
	ds_write_b32 v84, v68
	s_waitcnt vmcnt(10)
	ds_write_b32 v85, v69
	s_waitcnt vmcnt(9)
	ds_write_b32 v86, v70
	s_waitcnt vmcnt(8)
	ds_write_b32 v87, v71
	s_waitcnt vmcnt(7)
	ds_write_b32 v88, v72
	s_waitcnt vmcnt(6)
	ds_write_b32 v89, v73
	s_waitcnt vmcnt(5)
	ds_write_b32 v90, v74
	s_waitcnt vmcnt(4)
	ds_write_b32 v91, v75
	s_waitcnt vmcnt(3)
	ds_write_b32 v92, v76
	s_waitcnt vmcnt(2)
	ds_write_b32 v93, v77
	s_waitcnt vmcnt(1)
	ds_write_b32 v94, v78
	s_waitcnt vmcnt(0)
	ds_write_b32 v95, v79
	s_cbranch_scc1 .LBB0_1729
; #define GAS __attribute__((address_space(1)))
; #define LAS __attribute__((address_space(3)))
; __device__ __forceinline__ unsigned cvt_pk_bf16(float lo, float hi) { unsigned r; asm volatile("v_cvt_pk_bf16_f32 %0, %1, %2" : "=v"(r) : "v"(lo), "v"(hi)); return r; }
; #define LDS_WAIT() asm volatile("s_waitcnt lgkmcnt(0)" ::: "memory")
; __device__ __forceinline__ void cvt_job(const Frame& F, const float* W, int K, int Nsrc, bf16_t* dst, int nrows, int mode, float scale, const float* gain = nullptr) {
;     ...
;         LDS_WAIT(); asm volatile("" ::: "memory");
;         const int c = lane & 7;
; #pragma unroll
;         for (int j = 0; j < 4; ++j) { const int n = (lane >> 3) + 8 * j; const LAS float* s = scr + (8 * c) * 33 + n;
;             u32x4 o; o.x = cvt_pk_bf16(s[0 * 33], s[1 * 33]); o.y = cvt_pk_bf16(s[2 * 33], s[3 * 33]); o.z = cvt_pk_bf16(s[4 * 33], s[5 * 33]); o.w = cvt_pk_bf16(s[6 * 33], s[7 * 33]);
;             *(GAS u32x4*)(dst + (size_t)(n0 + n) * K + k0 + 8 * c) = o; }
;         LDS_WAIT(); asm volatile("" ::: "memory");
	s_waitcnt lgkmcnt(0)
	ds_read2_b32 v[14:15], v9 offset1:33
	s_waitcnt lgkmcnt(0)
	v_cvt_pk_bf16_f32 v14, v14, v15
	ds_read2_b32 v[16:17], v9 offset0:66 offset1:99
	s_waitcnt lgkmcnt(0)
	v_cvt_pk_bf16_f32 v15, v16, v17
	ds_read2_b32 v[16:17], v9 offset0:132 offset1:165
	s_waitcnt lgkmcnt(0)
	v_cvt_pk_bf16_f32 v16, v16, v17
	ds_read2_b32 v[18:19], v9 offset0:198 offset1:231
	s_waitcnt lgkmcnt(0)
	v_cvt_pk_bf16_f32 v17, v18, v19
	v_or_b32_e32 v18, s34, v8
	s_ashr_i32 s31, s30, 31
	v_ashrrev_i32_e32 v19, 31, v18
	v_lshl_add_u64 v[6:7], s[30:31], 1, v[4:5]
	v_lshlrev_b64 v[18:19], 13, v[18:19]
	v_lshl_add_u64 v[18:19], v[6:7], 0, v[18:19]
	global_store_dwordx4 v[18:19], v[14:17], off
	ds_read2_b32 v[14:15], v9 offset0:8 offset1:41
	s_add_i32 s12, s15, 0x680
	s_waitcnt lgkmcnt(0)
	v_cvt_pk_bf16_f32 v14, v14, v15
	ds_read2_b32 v[16:17], v9 offset0:74 offset1:107
	s_waitcnt lgkmcnt(0)
	v_cvt_pk_bf16_f32 v15, v16, v17
	ds_read2_b32 v[16:17], v9 offset0:140 offset1:173
	s_waitcnt lgkmcnt(0)
	v_cvt_pk_bf16_f32 v16, v16, v17
	ds_read2_b32 v[18:19], v9 offset0:206 offset1:239
	s_waitcnt lgkmcnt(0)
	v_cvt_pk_bf16_f32 v17, v18, v19
	v_or_b32_e32 v18, s34, v10
	v_ashrrev_i32_e32 v19, 31, v18
	v_lshlrev_b64 v[18:19], 13, v[18:19]
	v_lshl_add_u64 v[18:19], v[6:7], 0, v[18:19]
	global_store_dwordx4 v[18:19], v[14:17], off
	ds_read2_b32 v[14:15], v9 offset0:16 offset1:49
	s_cmpk_gt_i32 s15, 0x97f
	s_waitcnt lgkmcnt(0)
	v_cvt_pk_bf16_f32 v14, v14, v15
	ds_read2_b32 v[16:17], v9 offset0:82 offset1:115
	s_waitcnt lgkmcnt(0)
	v_cvt_pk_bf16_f32 v15, v16, v17
	ds_read2_b32 v[16:17], v9 offset0:148 offset1:181
	s_waitcnt lgkmcnt(0)
	v_cvt_pk_bf16_f32 v16, v16, v17
	ds_read2_b32 v[18:19], v9 offset0:214 offset1:247
	s_waitcnt lgkmcnt(0)
	v_cvt_pk_bf16_f32 v17, v18, v19
	v_or_b32_e32 v18, s34, v11
	v_ashrrev_i32_e32 v19, 31, v18
	v_lshlrev_b64 v[18:19], 13, v[18:19]
	v_lshl_add_u64 v[18:19], v[6:7], 0, v[18:19]
	global_store_dwordx4 v[18:19], v[14:17], off
	ds_read2_b32 v[14:15], v9 offset0:24 offset1:57
	s_mov_b32 s15, s12
	s_waitcnt lgkmcnt(0)
	v_cvt_pk_bf16_f32 v14, v14, v15
	ds_read2_b32 v[16:17], v9 offset0:90 offset1:123
	s_waitcnt lgkmcnt(0)
	v_cvt_pk_bf16_f32 v15, v16, v17
	ds_read2_b32 v[16:17], v9 offset0:156 offset1:189
	s_waitcnt lgkmcnt(0)
	v_cvt_pk_bf16_f32 v16, v16, v17
	ds_read2_b32 v[18:19], v9 offset0:222 offset1:255
	s_waitcnt lgkmcnt(0)
	v_cvt_pk_bf16_f32 v17, v18, v19
	v_or_b32_e32 v18, s34, v12
	v_ashrrev_i32_e32 v19, 31, v18
	v_lshlrev_b64 v[18:19], 13, v[18:19]
	v_lshl_add_u64 v[6:7], v[6:7], 0, v[18:19]
	global_store_dwordx4 v[6:7], v[14:17], off
	s_waitcnt lgkmcnt(0)
	s_cbranch_scc0 .LBB0_1728

; __device__ __forceinline__ void cvt_job(const Frame& F, const float* W, int K, int Nsrc, bf16_t* dst, int nrows, int mode, float scale, const float* gain = nullptr) {
;     ...
;     for (int it = F.gw; it < nitems; it += F.NGW) {
;         const int kb = it / nblk, nb = it % nblk, k0 = 64 * kb, n0 = 32 * nb;
;         const int nsrc = map_col(mode, n0 + (lane & 31));
; #pragma unroll 8
;         for (int i = 0; i < 32; ++i) { const int kk = 2 * i + (lane >> 5); scr[kk * 33 + (lane & 31)] = (mode == MAP_ZERO) ? 0.f : W[(size_t)(k0 + kk) * Nsrc + nsrc] * (gain ? scale * gain[k0 + kk] : scale); }
.LBB0_1790:
	s_lshl_b32 s41, s36, 1
	s_lshl_b32 s40, s31, 1
	v_or_b32_e32 v18, s41, v0
	v_or_b32_e32 v13, s40, v1
	v_add_u32_e32 v16, s30, v18
	v_add_u32_e32 v14, s35, v13
	v_ashrrev_i32_e32 v17, 31, v16
	v_ashrrev_i32_e32 v15, 31, v14
	v_lshlrev_b64 v[16:17], 14, v[16:17]
	v_lshlrev_b64 v[14:15], 14, v[14:15]
	v_lshl_add_u64 v[16:17], v[6:7], 0, v[16:17]
	v_lshl_add_u64 v[14:15], v[6:7], 0, v[14:15]
	global_load_dword v64, v[16:17], off
	global_load_dword v65, v[14:15], off
	v_mad_u64_u32 v[14:15], s[12:13], v18, s21, v[2:3]
	v_mad_u64_u32 v[16:17], s[12:13], v13, s21, v[2:3]
	s_add_i32 s13, s41, 4
	s_add_i32 s12, s40, 4
	v_or_b32_e32 v18, s13, v0
	v_or_b32_e32 v13, s12, v1
	s_add_i32 s36, s36, 16
	s_add_i32 s31, s31, 16
	s_add_i32 s37, s37, -16
	v_mov_b32_e32 v80, v14
	v_mov_b32_e32 v81, v16
	v_add_u32_e32 v16, s30, v18
	v_add_u32_e32 v14, s35, v13
	v_ashrrev_i32_e32 v17, 31, v16
	v_ashrrev_i32_e32 v15, 31, v14
	v_lshlrev_b64 v[16:17], 14, v[16:17]
	v_lshlrev_b64 v[14:15], 14, v[14:15]
	v_lshl_add_u64 v[16:17], v[6:7], 0, v[16:17]
	v_lshl_add_u64 v[14:15], v[6:7], 0, v[14:15]
	global_load_dword v66, v[16:17], off
	global_load_dword v67, v[14:15], off
	v_mad_u64_u32 v[14:15], s[12:13], v18, s21, v[2:3]
	v_mad_u64_u32 v[16:17], s[12:13], v13, s21, v[2:3]
	s_add_i32 s13, s41, 8
	s_add_i32 s12, s40, 8
	v_or_b32_e32 v18, s13, v0
	v_or_b32_e32 v13, s12, v1
	v_mov_b32_e32 v82, v14
	v_mov_b32_e32 v83, v16
	v_add_u32_e32 v16, s30, v18
	v_add_u32_e32 v14, s35, v13
	v_ashrrev_i32_e32 v17, 31, v16
	v_ashrrev_i32_e32 v15, 31, v14
	v_lshlrev_b64 v[16:17], 14, v[16:17]
	v_lshlrev_b64 v[14:15], 14, v[14:15]
	v_lshl_add_u64 v[16:17], v[6:7], 0, v[16:17]
	v_lshl_add_u64 v[14:15], v[6:7], 0, v[14:15]
	global_load_dword v68, v[16:17], off
	global_load_dword v69, v[14:15], off
	v_mad_u64_u32 v[14:15], s[12:13], v18, s21, v[2:3]
	v_mad_u64_u32 v[16:17], s[12:13], v13, s21, v[2:3]
	s_add_i32 s13, s41, 12
	s_add_i32 s12, s40, 12
	v_or_b32_e32 v18, s13, v0
	v_or_b32_e32 v13, s12, v1
	v_mov_b32_e32 v84, v14
	v_mov_b32_e32 v85, v16
	v_add_u32_e32 v16, s30, v18
	v_add_u32_e32 v14, s35, v13
	v_ashrrev_i32_e32 v17, 31, v16
	v_ashrrev_i32_e32 v15, 31, v14
	v_lshlrev_b64 v[16:17], 14, v[16:17]
	v_lshlrev_b64 v[14:15], 14, v[14:15]
	v_lshl_add_u64 v[16:17], v[6:7], 0, v[16:17]
	v_lshl_add_u64 v[14:15], v[6:7], 0, v[14:15]
	global_load_dword v70, v[16:17], off
	global_load_dword v71, v[14:15], off
	v_mad_u64_u32 v[14:15], s[12:13], v18, s21, v[2:3]
	v_mad_u64_u32 v[16:17], s[12:13], v13, s21, v[2:3]
	s_add_i32 s13, s41, 16
	s_add_i32 s12, s40, 16
	v_or_b32_e32 v18, s13, v0
	v_or_b32_e32 v13, s12, v1
	v_mov_b32_e32 v86, v14
	v_mov_b32_e32 v87, v16
	v_add_u32_e32 v16, s30, v18
	v_add_u32_e32 v14, s35, v13
	v_ashrrev_i32_e32 v17, 31, v16
	v_ashrrev_i32_e32 v15, 31, v14
	v_lshlrev_b64 v[16:17], 14, v[16:17]
	v_lshlrev_b64 v[14:15], 14, v[14:15]
	v_lshl_add_u64 v[16:17], v[6:7], 0, v[16:17]
	v_lshl_add_u64 v[14:15], v[6:7], 0, v[14:15]
	global_load_dword v72, v[16:17], off
	global_load_dword v73, v[14:15], off
	v_mad_u64_u32 v[14:15], s[12:13], v18, s21, v[2:3]
	v_mad_u64_u32 v[16:17], s[12:13], v13, s21, v[2:3]
	s_add_i32 s13, s41, 20
	s_add_i32 s12, s40, 20
	v_or_b32_e32 v18, s13, v0
	v_or_b32_e32 v13, s12, v1
	v_mov_b32_e32 v88, v14
	v_mov_b32_e32 v89, v16
	v_add_u32_e32 v16, s30, v18
	v_add_u32_e32 v14, s35, v13
	v_ashrrev_i32_e32 v17, 31, v16
	v_ashrrev_i32_e32 v15, 31, v14
	v_lshlrev_b64 v[16:17], 14, v[16:17]
	v_lshlrev_b64 v[14:15], 14, v[14:15]
	v_lshl_add_u64 v[16:17], v[6:7], 0, v[16:17]
	v_lshl_add_u64 v[14:15], v[6:7], 0, v[14:15]
	global_load_dword v74, v[16:17], off
	global_load_dword v75, v[14:15], off
	v_mad_u64_u32 v[14:15], s[12:13], v18, s21, v[2:3]
	v_mad_u64_u32 v[16:17], s[12:13], v13, s21, v[2:3]
	s_add_i32 s13, s41, 24
	s_add_i32 s12, s40, 24
	v_or_b32_e32 v18, s13, v0
	v_or_b32_e32 v13, s12, v1
	s_add_i32 s41, s41, 28
	s_add_i32 s40, s40, 28
	s_cmp_lg_u32 s37, 0
	v_mov_b32_e32 v90, v14
	v_mov_b32_e32 v91, v16
	v_add_u32_e32 v16, s30, v18
	v_add_u32_e32 v14, s35, v13
	v_ashrrev_i32_e32 v17, 31, v16
	v_ashrrev_i32_e32 v15, 31, v14
	v_lshlrev_b64 v[16:17], 14, v[16:17]
	v_lshlrev_b64 v[14:15], 14, v[14:15]
	v_lshl_add_u64 v[16:17], v[6:7], 0, v[16:17]
	v_lshl_add_u64 v[14:15], v[6:7], 0, v[14:15]
	global_load_dword v76, v[16:17], off
	global_load_dword v77, v[14:15], off
	v_mad_u64_u32 v[14:15], s[12:13], v18, s21, v[2:3]
	v_mad_u64_u32 v[16:17], s[12:13], v13, s21, v[2:3]
	v_or_b32_e32 v18, s41, v0
	v_or_b32_e32 v13, s40, v1
	v_mov_b32_e32 v92, v14
	v_mov_b32_e32 v93, v16
	v_add_u32_e32 v16, s30, v18
	v_add_u32_e32 v14, s35, v13
	v_ashrrev_i32_e32 v17, 31, v16
	v_ashrrev_i32_e32 v15, 31, v14
	v_lshlrev_b64 v[16:17], 14, v[16:17]
	v_lshlrev_b64 v[14:15], 14, v[14:15]
	v_lshl_add_u64 v[16:17], v[6:7], 0, v[16:17]
	v_lshl_add_u64 v[14:15], v[6:7], 0, v[14:15]
	global_load_dword v78, v[16:17], off
	global_load_dword v79, v[14:15], off
	v_mad_u64_u32 v[14:15], s[12:13], v18, s21, v[2:3]
	v_mad_u64_u32 v[16:17], s[12:13], v13, s21, v[2:3]
	v_mov_b32_e32 v94, v14
	v_mov_b32_e32 v95, v16
	s_waitcnt vmcnt(15)
	ds_write_b32 v80, v64
	s_waitcnt vmcnt(14)
	ds_write_b32 v81, v65
	s_waitcnt vmcnt(13)
	ds_write_b32 v82, v66
	s_waitcnt vmcnt(12)
	ds_write_b32 v83, v67
	s_waitcnt vmcnt(11)
	ds_write_b32 v84, v68
	s_waitcnt vmcnt(10)
	ds_write_b32 v85, v69
	s_waitcnt vmcnt(9)
	ds_write_b32 v86, v70
	s_waitcnt vmcnt(8)
	ds_write_b32 v87, v71
	s_waitcnt vmcnt(7)
	ds_write_b32 v88, v72
	s_waitcnt vmcnt(6)
	ds_write_b32 v89, v73
	s_waitcnt vmcnt(5)
	ds_write_b32 v90, v74
	s_waitcnt vmcnt(4)
	ds_write_b32 v91, v75
	s_waitcnt vmcnt(3)
	ds_write_b32 v92, v76
	s_waitcnt vmcnt(2)
	ds_write_b32 v93, v77
	s_waitcnt vmcnt(1)
	ds_write_b32 v94, v78
	s_waitcnt vmcnt(0)
	ds_write_b32 v95, v79
	s_cbranch_scc1 .LBB0_1790
; #define GAS __attribute__((address_space(1)))
; #define LAS __attribute__((address_space(3)))
; __device__ __forceinline__ unsigned cvt_pk_bf16(float lo, float hi) { unsigned r; asm volatile("v_cvt_pk_bf16_f32 %0, %1, %2" : "=v"(r) : "v"(lo), "v"(hi)); return r; }
; #define LDS_WAIT() asm volatile("s_waitcnt lgkmcnt(0)" ::: "memory")
; __device__ __forceinline__ void cvt_job(const Frame& F, const float* W, int K, int Nsrc, bf16_t* dst, int nrows, int mode, float scale, const float* gain = nullptr) {
;     ...
;         LDS_WAIT(); asm volatile("" ::: "memory");
;         const int c = lane & 7;
; #pragma unroll
;         for (int j = 0; j < 4; ++j) { const int n = (lane >> 3) + 8 * j; const LAS float* s = scr + (8 * c) * 33 + n;
;             u32x4 o; o.x = cvt_pk_bf16(s[0 * 33], s[1 * 33]); o.y = cvt_pk_bf16(s[2 * 33], s[3 * 33]); o.z = cvt_pk_bf16(s[4 * 33], s[5 * 33]); o.w = cvt_pk_bf16(s[6 * 33], s[7 * 33]);
;             *(GAS u32x4*)(dst + (size_t)(n0 + n) * K + k0 + 8 * c) = o; }
;         LDS_WAIT(); asm volatile("" ::: "memory");
	s_waitcnt lgkmcnt(0)
	ds_read2_b32 v[14:15], v9 offset1:33
	s_waitcnt lgkmcnt(0)
	v_cvt_pk_bf16_f32 v14, v14, v15
	ds_read2_b32 v[16:17], v9 offset0:66 offset1:99
	s_waitcnt lgkmcnt(0)
	v_cvt_pk_bf16_f32 v15, v16, v17
	ds_read2_b32 v[16:17], v9 offset0:132 offset1:165
	s_waitcnt lgkmcnt(0)
	v_cvt_pk_bf16_f32 v16, v16, v17
	ds_read2_b32 v[18:19], v9 offset0:198 offset1:231
	s_waitcnt lgkmcnt(0)
	v_cvt_pk_bf16_f32 v17, v18, v19
	v_or_b32_e32 v18, s34, v8
	s_ashr_i32 s31, s30, 31
	v_ashrrev_i32_e32 v19, 31, v18
	v_lshl_add_u64 v[6:7], s[30:31], 1, v[4:5]
	v_lshlrev_b64 v[18:19], 10, v[18:19]
	v_lshl_add_u64 v[18:19], v[6:7], 0, v[18:19]
	global_store_dwordx4 v[18:19], v[14:17], off
	ds_read2_b32 v[14:15], v9 offset0:8 offset1:41
	s_add_i32 s12, s15, 0x680
	s_waitcnt lgkmcnt(0)
	v_cvt_pk_bf16_f32 v14, v14, v15
	ds_read2_b32 v[16:17], v9 offset0:74 offset1:107
	s_waitcnt lgkmcnt(0)
	v_cvt_pk_bf16_f32 v15, v16, v17
	ds_read2_b32 v[16:17], v9 offset0:140 offset1:173
	s_waitcnt lgkmcnt(0)
	v_cvt_pk_bf16_f32 v16, v16, v17
	ds_read2_b32 v[18:19], v9 offset0:206 offset1:239
	s_waitcnt lgkmcnt(0)
	v_cvt_pk_bf16_f32 v17, v18, v19
	v_or_b32_e32 v18, s34, v10
	v_ashrrev_i32_e32 v19, 31, v18
	v_lshlrev_b64 v[18:19], 10, v[18:19]
	v_lshl_add_u64 v[18:19], v[6:7], 0, v[18:19]
	global_store_dwordx4 v[18:19], v[14:17], off
	ds_read2_b32 v[14:15], v9 offset0:16 offset1:49
	s_cmpk_lt_i32 s15, 0xfd80
	s_waitcnt lgkmcnt(0)
	v_cvt_pk_bf16_f32 v14, v14, v15
	ds_read2_b32 v[16:17], v9 offset0:82 offset1:115
	s_waitcnt lgkmcnt(0)
	v_cvt_pk_bf16_f32 v15, v16, v17
	ds_read2_b32 v[16:17], v9 offset0:148 offset1:181
	s_waitcnt lgkmcnt(0)
	v_cvt_pk_bf16_f32 v16, v16, v17
	ds_read2_b32 v[18:19], v9 offset0:214 offset1:247
	s_waitcnt lgkmcnt(0)
	v_cvt_pk_bf16_f32 v17, v18, v19
	v_or_b32_e32 v18, s34, v11
	v_ashrrev_i32_e32 v19, 31, v18
	v_lshlrev_b64 v[18:19], 10, v[18:19]
	v_lshl_add_u64 v[18:19], v[6:7], 0, v[18:19]
	global_store_dwordx4 v[18:19], v[14:17], off
	ds_read2_b32 v[14:15], v9 offset0:24 offset1:57
	s_mov_b32 s15, s12
	s_waitcnt lgkmcnt(0)
	v_cvt_pk_bf16_f32 v14, v14, v15
	ds_read2_b32 v[16:17], v9 offset0:90 offset1:123
	s_waitcnt lgkmcnt(0)
	v_cvt_pk_bf16_f32 v15, v16, v17
	ds_read2_b32 v[16:17], v9 offset0:156 offset1:189
	s_waitcnt lgkmcnt(0)
	v_cvt_pk_bf16_f32 v16, v16, v17
	ds_read2_b32 v[18:19], v9 offset0:222 offset1:255
	s_waitcnt lgkmcnt(0)
	v_cvt_pk_bf16_f32 v17, v18, v19
	v_or_b32_e32 v18, s34, v12
	v_ashrrev_i32_e32 v19, 31, v18
	v_lshlrev_b64 v[18:19], 10, v[18:19]
	v_lshl_add_u64 v[6:7], v[6:7], 0, v[18:19]
	global_store_dwordx4 v[6:7], v[14:17], off
	s_waitcnt lgkmcnt(0)
	s_cbranch_scc1 .LBB0_1789

; __device__ __forceinline__ void cvt_job(const Frame& F, const float* W, int K, int Nsrc, bf16_t* dst, int nrows, int mode, float scale, const float* gain = nullptr) {
;     ...
;     for (int it = F.gw; it < nitems; it += F.NGW) {
;         const int kb = it / nblk, nb = it % nblk, k0 = 64 * kb, n0 = 32 * nb;
;         const int nsrc = map_col(mode, n0 + (lane & 31));
; #pragma unroll 8
;         for (int i = 0; i < 32; ++i) { const int kk = 2 * i + (lane >> 5); scr[kk * 33 + (lane & 31)] = (mode == MAP_ZERO) ? 0.f : W[(size_t)(k0 + kk) * Nsrc + nsrc] * (gain ? scale * gain[k0 + kk] : scale); }
.LBB0_1795:
	s_lshl_b32 s39, s36, 1
	s_lshl_b32 s38, s35, 1
	v_or_b32_e32 v18, s39, v0
	v_or_b32_e32 v13, s38, v1
	v_add_u32_e32 v16, s30, v18
	v_add_u32_e32 v14, s31, v13
	v_ashrrev_i32_e32 v17, 31, v16
	v_ashrrev_i32_e32 v15, 31, v14
	v_lshlrev_b64 v[16:17], 13, v[16:17]
	v_lshlrev_b64 v[14:15], 13, v[14:15]
	v_lshl_add_u64 v[16:17], v[6:7], 0, v[16:17]
	v_lshl_add_u64 v[14:15], v[6:7], 0, v[14:15]
	global_load_dword v64, v[16:17], off
	global_load_dword v65, v[14:15], off
	v_mad_u64_u32 v[14:15], s[12:13], v18, s21, v[2:3]
	v_mad_u64_u32 v[16:17], s[12:13], v13, s21, v[2:3]
	s_add_i32 s13, s39, 4
	s_add_i32 s12, s38, 4
	v_or_b32_e32 v18, s13, v0
	v_or_b32_e32 v13, s12, v1
	s_add_i32 s36, s36, 16
	s_add_i32 s35, s35, 16
	s_add_i32 s37, s37, -16
	v_mov_b32_e32 v80, v14
	v_mov_b32_e32 v81, v16
	v_add_u32_e32 v16, s30, v18
	v_add_u32_e32 v14, s31, v13
	v_ashrrev_i32_e32 v17, 31, v16
	v_ashrrev_i32_e32 v15, 31, v14
	v_lshlrev_b64 v[16:17], 13, v[16:17]
	v_lshlrev_b64 v[14:15], 13, v[14:15]
	v_lshl_add_u64 v[16:17], v[6:7], 0, v[16:17]
	v_lshl_add_u64 v[14:15], v[6:7], 0, v[14:15]
	global_load_dword v66, v[16:17], off
	global_load_dword v67, v[14:15], off
	v_mad_u64_u32 v[14:15], s[12:13], v18, s21, v[2:3]
	v_mad_u64_u32 v[16:17], s[12:13], v13, s21, v[2:3]
	s_add_i32 s13, s39, 8
	s_add_i32 s12, s38, 8
	v_or_b32_e32 v18, s13, v0
	v_or_b32_e32 v13, s12, v1
	v_mov_b32_e32 v82, v14
	v_mov_b32_e32 v83, v16
	v_add_u32_e32 v16, s30, v18
	v_add_u32_e32 v14, s31, v13
	v_ashrrev_i32_e32 v17, 31, v16
	v_ashrrev_i32_e32 v15, 31, v14
	v_lshlrev_b64 v[16:17], 13, v[16:17]
	v_lshlrev_b64 v[14:15], 13, v[14:15]
	v_lshl_add_u64 v[16:17], v[6:7], 0, v[16:17]
	v_lshl_add_u64 v[14:15], v[6:7], 0, v[14:15]
	global_load_dword v68, v[16:17], off
	global_load_dword v69, v[14:15], off
	v_mad_u64_u32 v[14:15], s[12:13], v18, s21, v[2:3]
	v_mad_u64_u32 v[16:17], s[12:13], v13, s21, v[2:3]
	s_add_i32 s13, s39, 12
	s_add_i32 s12, s38, 12
	v_or_b32_e32 v18, s13, v0
	v_or_b32_e32 v13, s12, v1
	v_mov_b32_e32 v84, v14
	v_mov_b32_e32 v85, v16
	v_add_u32_e32 v16, s30, v18
	v_add_u32_e32 v14, s31, v13
	v_ashrrev_i32_e32 v17, 31, v16
	v_ashrrev_i32_e32 v15, 31, v14
	v_lshlrev_b64 v[16:17], 13, v[16:17]
	v_lshlrev_b64 v[14:15], 13, v[14:15]
	v_lshl_add_u64 v[16:17], v[6:7], 0, v[16:17]
	v_lshl_add_u64 v[14:15], v[6:7], 0, v[14:15]
	global_load_dword v70, v[16:17], off
	global_load_dword v71, v[14:15], off
	v_mad_u64_u32 v[14:15], s[12:13], v18, s21, v[2:3]
	v_mad_u64_u32 v[16:17], s[12:13], v13, s21, v[2:3]
	s_add_i32 s13, s39, 16
	s_add_i32 s12, s38, 16
	v_or_b32_e32 v18, s13, v0
	v_or_b32_e32 v13, s12, v1
	v_mov_b32_e32 v86, v14
	v_mov_b32_e32 v87, v16
	v_add_u32_e32 v16, s30, v18
	v_add_u32_e32 v14, s31, v13
	v_ashrrev_i32_e32 v17, 31, v16
	v_ashrrev_i32_e32 v15, 31, v14
	v_lshlrev_b64 v[16:17], 13, v[16:17]
	v_lshlrev_b64 v[14:15], 13, v[14:15]
	v_lshl_add_u64 v[16:17], v[6:7], 0, v[16:17]
	v_lshl_add_u64 v[14:15], v[6:7], 0, v[14:15]
	global_load_dword v72, v[16:17], off
	global_load_dword v73, v[14:15], off
	v_mad_u64_u32 v[14:15], s[12:13], v18, s21, v[2:3]
	v_mad_u64_u32 v[16:17], s[12:13], v13, s21, v[2:3]
	s_add_i32 s13, s39, 20
	s_add_i32 s12, s38, 20
	v_or_b32_e32 v18, s13, v0
	v_or_b32_e32 v13, s12, v1
	v_mov_b32_e32 v88, v14
	v_mov_b32_e32 v89, v16
	v_add_u32_e32 v16, s30, v18
	v_add_u32_e32 v14, s31, v13
	v_ashrrev_i32_e32 v17, 31, v16
	v_ashrrev_i32_e32 v15, 31, v14
	v_lshlrev_b64 v[16:17], 13, v[16:17]
	v_lshlrev_b64 v[14:15], 13, v[14:15]
	v_lshl_add_u64 v[16:17], v[6:7], 0, v[16:17]
	v_lshl_add_u64 v[14:15], v[6:7], 0, v[14:15]
	global_load_dword v74, v[16:17], off
	global_load_dword v75, v[14:15], off
	v_mad_u64_u32 v[14:15], s[12:13], v18, s21, v[2:3]
	v_mad_u64_u32 v[16:17], s[12:13], v13, s21, v[2:3]
	s_add_i32 s13, s39, 24
	s_add_i32 s12, s38, 24
	v_or_b32_e32 v18, s13, v0
	v_or_b32_e32 v13, s12, v1
	s_add_i32 s39, s39, 28
	s_add_i32 s38, s38, 28
	s_cmp_lg_u32 s37, 0
	v_mov_b32_e32 v90, v14
	v_mov_b32_e32 v91, v16
	v_add_u32_e32 v16, s30, v18
	v_add_u32_e32 v14, s31, v13
	v_ashrrev_i32_e32 v17, 31, v16
	v_ashrrev_i32_e32 v15, 31, v14
	v_lshlrev_b64 v[16:17], 13, v[16:17]
	v_lshlrev_b64 v[14:15], 13, v[14:15]
	v_lshl_add_u64 v[16:17], v[6:7], 0, v[16:17]
	v_lshl_add_u64 v[14:15], v[6:7], 0, v[14:15]
	global_load_dword v76, v[16:17], off
	global_load_dword v77, v[14:15], off
	v_mad_u64_u32 v[14:15], s[12:13], v18, s21, v[2:3]
	v_mad_u64_u32 v[16:17], s[12:13], v13, s21, v[2:3]
	v_or_b32_e32 v18, s39, v0
	v_or_b32_e32 v13, s38, v1
	v_mov_b32_e32 v92, v14
	v_mov_b32_e32 v93, v16
	v_add_u32_e32 v16, s30, v18
	v_add_u32_e32 v14, s31, v13
	v_ashrrev_i32_e32 v17, 31, v16
	v_ashrrev_i32_e32 v15, 31, v14
	v_lshlrev_b64 v[16:17], 13, v[16:17]
	v_lshlrev_b64 v[14:15], 13, v[14:15]
	v_lshl_add_u64 v[16:17], v[6:7], 0, v[16:17]
	v_lshl_add_u64 v[14:15], v[6:7], 0, v[14:15]
	global_load_dword v78, v[16:17], off
	global_load_dword v79, v[14:15], off
	v_mad_u64_u32 v[14:15], s[12:13], v18, s21, v[2:3]
	v_mad_u64_u32 v[16:17], s[12:13], v13, s21, v[2:3]
	v_mov_b32_e32 v94, v14
	v_mov_b32_e32 v95, v16
	s_waitcnt vmcnt(15)
	ds_write_b32 v80, v64
	s_waitcnt vmcnt(14)
	ds_write_b32 v81, v65
	s_waitcnt vmcnt(13)
	ds_write_b32 v82, v66
	s_waitcnt vmcnt(12)
	ds_write_b32 v83, v67
	s_waitcnt vmcnt(11)
	ds_write_b32 v84, v68
	s_waitcnt vmcnt(10)
	ds_write_b32 v85, v69
	s_waitcnt vmcnt(9)
	ds_write_b32 v86, v70
	s_waitcnt vmcnt(8)
	ds_write_b32 v87, v71
	s_waitcnt vmcnt(7)
	ds_write_b32 v88, v72
	s_waitcnt vmcnt(6)
	ds_write_b32 v89, v73
	s_waitcnt vmcnt(5)
	ds_write_b32 v90, v74
	s_waitcnt vmcnt(4)
	ds_write_b32 v91, v75
	s_waitcnt vmcnt(3)
	ds_write_b32 v92, v76
	s_waitcnt vmcnt(2)
	ds_write_b32 v93, v77
	s_waitcnt vmcnt(1)
	ds_write_b32 v94, v78
	s_waitcnt vmcnt(0)
	ds_write_b32 v95, v79
	s_cbranch_scc1 .LBB0_1795
; #define GAS __attribute__((address_space(1)))
; #define LAS __attribute__((address_space(3)))
; __device__ __forceinline__ unsigned cvt_pk_bf16(float lo, float hi) { unsigned r; asm volatile("v_cvt_pk_bf16_f32 %0, %1, %2" : "=v"(r) : "v"(lo), "v"(hi)); return r; }
; #define LDS_WAIT() asm volatile("s_waitcnt lgkmcnt(0)" ::: "memory")
; __device__ __forceinline__ void cvt_job(const Frame& F, const float* W, int K, int Nsrc, bf16_t* dst, int nrows, int mode, float scale, const float* gain = nullptr) {
;     ...
;         LDS_WAIT(); asm volatile("" ::: "memory");
;         const int c = lane & 7;
; #pragma unroll
;         for (int j = 0; j < 4; ++j) { const int n = (lane >> 3) + 8 * j; const LAS float* s = scr + (8 * c) * 33 + n;
;             u32x4 o; o.x = cvt_pk_bf16(s[0 * 33], s[1 * 33]); o.y = cvt_pk_bf16(s[2 * 33], s[3 * 33]); o.z = cvt_pk_bf16(s[4 * 33], s[5 * 33]); o.w = cvt_pk_bf16(s[6 * 33], s[7 * 33]);
;             *(GAS u32x4*)(dst + (size_t)(n0 + n) * K + k0 + 8 * c) = o; }
;         LDS_WAIT(); asm volatile("" ::: "memory");
	s_waitcnt lgkmcnt(0)
	ds_read2_b32 v[14:15], v9 offset1:33
	s_waitcnt lgkmcnt(0)
	v_cvt_pk_bf16_f32 v14, v14, v15
	ds_read2_b32 v[16:17], v9 offset0:66 offset1:99
	s_waitcnt lgkmcnt(0)
	v_cvt_pk_bf16_f32 v15, v16, v17
	ds_read2_b32 v[16:17], v9 offset0:132 offset1:165
	s_waitcnt lgkmcnt(0)
	v_cvt_pk_bf16_f32 v16, v16, v17
	ds_read2_b32 v[18:19], v9 offset0:198 offset1:231
	s_waitcnt lgkmcnt(0)
	v_cvt_pk_bf16_f32 v17, v18, v19
	v_or_b32_e32 v18, s34, v8
	s_ashr_i32 s31, s30, 31
	v_ashrrev_i32_e32 v19, 31, v18
	v_lshl_add_u64 v[6:7], s[30:31], 1, v[4:5]
	v_lshlrev_b64 v[18:19], 12, v[18:19]
	v_lshl_add_u64 v[18:19], v[6:7], 0, v[18:19]
	global_store_dwordx4 v[18:19], v[14:17], off
	ds_read2_b32 v[14:15], v9 offset0:8 offset1:41
	s_add_i32 s12, s15, 0x680
	s_waitcnt lgkmcnt(0)
	v_cvt_pk_bf16_f32 v14, v14, v15
	ds_read2_b32 v[16:17], v9 offset0:74 offset1:107
	s_waitcnt lgkmcnt(0)
	v_cvt_pk_bf16_f32 v15, v16, v17
	ds_read2_b32 v[16:17], v9 offset0:140 offset1:173
	s_waitcnt lgkmcnt(0)
	v_cvt_pk_bf16_f32 v16, v16, v17
	ds_read2_b32 v[18:19], v9 offset0:206 offset1:239
	s_waitcnt lgkmcnt(0)
	v_cvt_pk_bf16_f32 v17, v18, v19
	v_or_b32_e32 v18, s34, v10
	v_ashrrev_i32_e32 v19, 31, v18
	v_lshlrev_b64 v[18:19], 12, v[18:19]
	v_lshl_add_u64 v[18:19], v[6:7], 0, v[18:19]
	global_store_dwordx4 v[18:19], v[14:17], off
	ds_read2_b32 v[14:15], v9 offset0:16 offset1:49
	s_cmpk_gt_i32 s15, 0x17f
	s_waitcnt lgkmcnt(0)
	v_cvt_pk_bf16_f32 v14, v14, v15
	ds_read2_b32 v[16:17], v9 offset0:82 offset1:115
	s_waitcnt lgkmcnt(0)
	v_cvt_pk_bf16_f32 v15, v16, v17
	ds_read2_b32 v[16:17], v9 offset0:148 offset1:181
	s_waitcnt lgkmcnt(0)
	v_cvt_pk_bf16_f32 v16, v16, v17
	ds_read2_b32 v[18:19], v9 offset0:214 offset1:247
	s_waitcnt lgkmcnt(0)
	v_cvt_pk_bf16_f32 v17, v18, v19
	v_or_b32_e32 v18, s34, v11
	v_ashrrev_i32_e32 v19, 31, v18
	v_lshlrev_b64 v[18:19], 12, v[18:19]
	v_lshl_add_u64 v[18:19], v[6:7], 0, v[18:19]
	global_store_dwordx4 v[18:19], v[14:17], off
	ds_read2_b32 v[14:15], v9 offset0:24 offset1:57
	s_mov_b32 s15, s12
	s_waitcnt lgkmcnt(0)
	v_cvt_pk_bf16_f32 v14, v14, v15
	ds_read2_b32 v[16:17], v9 offset0:90 offset1:123
	s_waitcnt lgkmcnt(0)
	v_cvt_pk_bf16_f32 v15, v16, v17
	ds_read2_b32 v[16:17], v9 offset0:156 offset1:189
	s_waitcnt lgkmcnt(0)
	v_cvt_pk_bf16_f32 v16, v16, v17
	ds_read2_b32 v[18:19], v9 offset0:222 offset1:255
	s_waitcnt lgkmcnt(0)
	v_cvt_pk_bf16_f32 v17, v18, v19
	v_or_b32_e32 v18, s34, v12
	v_ashrrev_i32_e32 v19, 31, v18
	v_lshlrev_b64 v[18:19], 12, v[18:19]
	v_lshl_add_u64 v[6:7], v[6:7], 0, v[18:19]
	global_store_dwordx4 v[6:7], v[14:17], off
	s_waitcnt lgkmcnt(0)
	s_cbranch_scc0 .LBB0_1794

; __device__ __forceinline__ void cvt_job(const Frame& F, const float* W, int K, int Nsrc, bf16_t* dst, int nrows, int mode, float scale, const float* gain = nullptr) {
;     ...
;     for (int it = F.gw; it < nitems; it += F.NGW) {
;         const int kb = it / nblk, nb = it % nblk, k0 = 64 * kb, n0 = 32 * nb;
;         const int nsrc = map_col(mode, n0 + (lane & 31));
; #pragma unroll 8
;         for (int i = 0; i < 32; ++i) { const int kk = 2 * i + (lane >> 5); scr[kk * 33 + (lane & 31)] = (mode == MAP_ZERO) ? 0.f : W[(size_t)(k0 + kk) * Nsrc + nsrc] * (gain ? scale * gain[k0 + kk] : scale); }
.LBB0_1800:
	s_lshl_b32 s34, s29, 1
	s_lshl_b32 s31, s18, 1
	v_or_b32_e32 v18, s34, v0
	v_or_b32_e32 v13, s31, v1
	v_add_u32_e32 v16, s28, v18
	v_add_u32_e32 v14, s15, v13
	v_ashrrev_i32_e32 v17, 31, v16
	v_ashrrev_i32_e32 v15, 31, v14
	v_lshlrev_b64 v[16:17], 15, v[16:17]
	v_lshlrev_b64 v[14:15], 15, v[14:15]
	v_lshl_add_u64 v[16:17], v[6:7], 0, v[16:17]
	v_lshl_add_u64 v[14:15], v[6:7], 0, v[14:15]
	global_load_dword v64, v[16:17], off
	global_load_dword v65, v[14:15], off
	v_mad_u64_u32 v[14:15], s[12:13], v18, s21, v[2:3]
	v_mad_u64_u32 v[16:17], s[12:13], v13, s21, v[2:3]
	s_add_i32 s13, s34, 4
	s_add_i32 s12, s31, 4
	v_or_b32_e32 v18, s13, v0
	v_or_b32_e32 v13, s12, v1
	s_add_i32 s29, s29, 16
	s_add_i32 s18, s18, 16
	s_add_i32 s30, s30, -16
	v_mov_b32_e32 v80, v14
	v_mov_b32_e32 v81, v16
	v_add_u32_e32 v16, s28, v18
	v_add_u32_e32 v14, s15, v13
	v_ashrrev_i32_e32 v17, 31, v16
	v_ashrrev_i32_e32 v15, 31, v14
	v_lshlrev_b64 v[16:17], 15, v[16:17]
	v_lshlrev_b64 v[14:15], 15, v[14:15]
	v_lshl_add_u64 v[16:17], v[6:7], 0, v[16:17]
	v_lshl_add_u64 v[14:15], v[6:7], 0, v[14:15]
	global_load_dword v66, v[16:17], off
	global_load_dword v67, v[14:15], off
	v_mad_u64_u32 v[14:15], s[12:13], v18, s21, v[2:3]
	v_mad_u64_u32 v[16:17], s[12:13], v13, s21, v[2:3]
	s_add_i32 s13, s34, 8
	s_add_i32 s12, s31, 8
	v_or_b32_e32 v18, s13, v0
	v_or_b32_e32 v13, s12, v1
	v_mov_b32_e32 v82, v14
	v_mov_b32_e32 v83, v16
	v_add_u32_e32 v16, s28, v18
	v_add_u32_e32 v14, s15, v13
	v_ashrrev_i32_e32 v17, 31, v16
	v_ashrrev_i32_e32 v15, 31, v14
	v_lshlrev_b64 v[16:17], 15, v[16:17]
	v_lshlrev_b64 v[14:15], 15, v[14:15]
	v_lshl_add_u64 v[16:17], v[6:7], 0, v[16:17]
	v_lshl_add_u64 v[14:15], v[6:7], 0, v[14:15]
	global_load_dword v68, v[16:17], off
	global_load_dword v69, v[14:15], off
	v_mad_u64_u32 v[14:15], s[12:13], v18, s21, v[2:3]
	v_mad_u64_u32 v[16:17], s[12:13], v13, s21, v[2:3]
	s_add_i32 s13, s34, 12
	s_add_i32 s12, s31, 12
	v_or_b32_e32 v18, s13, v0
	v_or_b32_e32 v13, s12, v1
	v_mov_b32_e32 v84, v14
	v_mov_b32_e32 v85, v16
	v_add_u32_e32 v16, s28, v18
	v_add_u32_e32 v14, s15, v13
	v_ashrrev_i32_e32 v17, 31, v16
	v_ashrrev_i32_e32 v15, 31, v14
	v_lshlrev_b64 v[16:17], 15, v[16:17]
	v_lshlrev_b64 v[14:15], 15, v[14:15]
	v_lshl_add_u64 v[16:17], v[6:7], 0, v[16:17]
	v_lshl_add_u64 v[14:15], v[6:7], 0, v[14:15]
	global_load_dword v70, v[16:17], off
	global_load_dword v71, v[14:15], off
	v_mad_u64_u32 v[14:15], s[12:13], v18, s21, v[2:3]
	v_mad_u64_u32 v[16:17], s[12:13], v13, s21, v[2:3]
	s_add_i32 s13, s34, 16
	s_add_i32 s12, s31, 16
	v_or_b32_e32 v18, s13, v0
	v_or_b32_e32 v13, s12, v1
	v_mov_b32_e32 v86, v14
	v_mov_b32_e32 v87, v16
	v_add_u32_e32 v16, s28, v18
	v_add_u32_e32 v14, s15, v13
	v_ashrrev_i32_e32 v17, 31, v16
	v_ashrrev_i32_e32 v15, 31, v14
	v_lshlrev_b64 v[16:17], 15, v[16:17]
	v_lshlrev_b64 v[14:15], 15, v[14:15]
	v_lshl_add_u64 v[16:17], v[6:7], 0, v[16:17]
	v_lshl_add_u64 v[14:15], v[6:7], 0, v[14:15]
	global_load_dword v72, v[16:17], off
	global_load_dword v73, v[14:15], off
	v_mad_u64_u32 v[14:15], s[12:13], v18, s21, v[2:3]
	v_mad_u64_u32 v[16:17], s[12:13], v13, s21, v[2:3]
	s_add_i32 s13, s34, 20
	s_add_i32 s12, s31, 20
	v_or_b32_e32 v18, s13, v0
	v_or_b32_e32 v13, s12, v1
	v_mov_b32_e32 v88, v14
	v_mov_b32_e32 v89, v16
	v_add_u32_e32 v16, s28, v18
	v_add_u32_e32 v14, s15, v13
	v_ashrrev_i32_e32 v17, 31, v16
	v_ashrrev_i32_e32 v15, 31, v14
	v_lshlrev_b64 v[16:17], 15, v[16:17]
	v_lshlrev_b64 v[14:15], 15, v[14:15]
	v_lshl_add_u64 v[16:17], v[6:7], 0, v[16:17]
	v_lshl_add_u64 v[14:15], v[6:7], 0, v[14:15]
	global_load_dword v74, v[16:17], off
	global_load_dword v75, v[14:15], off
	v_mad_u64_u32 v[14:15], s[12:13], v18, s21, v[2:3]
	v_mad_u64_u32 v[16:17], s[12:13], v13, s21, v[2:3]
	s_add_i32 s13, s34, 24
	s_add_i32 s12, s31, 24
	v_or_b32_e32 v18, s13, v0
	v_or_b32_e32 v13, s12, v1
	s_add_i32 s34, s34, 28
	s_add_i32 s31, s31, 28
	s_cmp_lg_u32 s30, 0
	v_mov_b32_e32 v90, v14
	v_mov_b32_e32 v91, v16
	v_add_u32_e32 v16, s28, v18
	v_add_u32_e32 v14, s15, v13
	v_ashrrev_i32_e32 v17, 31, v16
	v_ashrrev_i32_e32 v15, 31, v14
	v_lshlrev_b64 v[16:17], 15, v[16:17]
	v_lshlrev_b64 v[14:15], 15, v[14:15]
	v_lshl_add_u64 v[16:17], v[6:7], 0, v[16:17]
	v_lshl_add_u64 v[14:15], v[6:7], 0, v[14:15]
	global_load_dword v76, v[16:17], off
	global_load_dword v77, v[14:15], off
	v_mad_u64_u32 v[14:15], s[12:13], v18, s21, v[2:3]
	v_mad_u64_u32 v[16:17], s[12:13], v13, s21, v[2:3]
	v_or_b32_e32 v18, s34, v0
	v_or_b32_e32 v13, s31, v1
	v_mov_b32_e32 v92, v14
	v_mov_b32_e32 v93, v16
	v_add_u32_e32 v16, s28, v18
	v_add_u32_e32 v14, s15, v13
	v_ashrrev_i32_e32 v17, 31, v16
	v_ashrrev_i32_e32 v15, 31, v14
	v_lshlrev_b64 v[16:17], 15, v[16:17]
	v_lshlrev_b64 v[14:15], 15, v[14:15]
	v_lshl_add_u64 v[16:17], v[6:7], 0, v[16:17]
	v_lshl_add_u64 v[14:15], v[6:7], 0, v[14:15]
	global_load_dword v78, v[16:17], off
	global_load_dword v79, v[14:15], off
	v_mad_u64_u32 v[14:15], s[12:13], v18, s21, v[2:3]
	v_mad_u64_u32 v[16:17], s[12:13], v13, s21, v[2:3]
	v_mov_b32_e32 v94, v14
	v_mov_b32_e32 v95, v16
	s_waitcnt vmcnt(15)
	ds_write_b32 v80, v64
	s_waitcnt vmcnt(14)
	ds_write_b32 v81, v65
	s_waitcnt vmcnt(13)
	ds_write_b32 v82, v66
	s_waitcnt vmcnt(12)
	ds_write_b32 v83, v67
	s_waitcnt vmcnt(11)
	ds_write_b32 v84, v68
	s_waitcnt vmcnt(10)
	ds_write_b32 v85, v69
	s_waitcnt vmcnt(9)
	ds_write_b32 v86, v70
	s_waitcnt vmcnt(8)
	ds_write_b32 v87, v71
	s_waitcnt vmcnt(7)
	ds_write_b32 v88, v72
	s_waitcnt vmcnt(6)
	ds_write_b32 v89, v73
	s_waitcnt vmcnt(5)
	ds_write_b32 v90, v74
	s_waitcnt vmcnt(4)
	ds_write_b32 v91, v75
	s_waitcnt vmcnt(3)
	ds_write_b32 v92, v76
	s_waitcnt vmcnt(2)
	ds_write_b32 v93, v77
	s_waitcnt vmcnt(1)
	ds_write_b32 v94, v78
	s_waitcnt vmcnt(0)
	ds_write_b32 v95, v79
	s_cbranch_scc1 .LBB0_1800
; #define GAS __attribute__((address_space(1)))
; #define LAS __attribute__((address_space(3)))
; __device__ __forceinline__ unsigned cvt_pk_bf16(float lo, float hi) { unsigned r; asm volatile("v_cvt_pk_bf16_f32 %0, %1, %2" : "=v"(r) : "v"(lo), "v"(hi)); return r; }
; #define LDS_WAIT() asm volatile("s_waitcnt lgkmcnt(0)" ::: "memory")
; __device__ __forceinline__ void cvt_job(const Frame& F, const float* W, int K, int Nsrc, bf16_t* dst, int nrows, int mode, float scale, const float* gain = nullptr) {
;     ...
;         LDS_WAIT(); asm volatile("" ::: "memory");
;         const int c = lane & 7;
; #pragma unroll
;         for (int j = 0; j < 4; ++j) { const int n = (lane >> 3) + 8 * j; const LAS float* s = scr + (8 * c) * 33 + n;
;             u32x4 o; o.x = cvt_pk_bf16(s[0 * 33], s[1 * 33]); o.y = cvt_pk_bf16(s[2 * 33], s[3 * 33]); o.z = cvt_pk_bf16(s[4 * 33], s[5 * 33]); o.w = cvt_pk_bf16(s[6 * 33], s[7 * 33]);
;             *(GAS u32x4*)(dst + (size_t)(n0 + n) * K + k0 + 8 * c) = o; }
;         LDS_WAIT(); asm volatile("" ::: "memory");
	s_waitcnt lgkmcnt(0)
	ds_read2_b32 v[14:15], v9 offset1:33
	s_waitcnt lgkmcnt(0)
	v_cvt_pk_bf16_f32 v14, v14, v15
	ds_read2_b32 v[16:17], v9 offset0:66 offset1:99
	s_waitcnt lgkmcnt(0)
	v_cvt_pk_bf16_f32 v15, v16, v17
	ds_read2_b32 v[16:17], v9 offset0:132 offset1:165
	s_waitcnt lgkmcnt(0)
	v_cvt_pk_bf16_f32 v16, v16, v17
	ds_read2_b32 v[18:19], v9 offset0:198 offset1:231
	s_waitcnt lgkmcnt(0)
	v_cvt_pk_bf16_f32 v17, v18, v19
	v_or_b32_e32 v18, s11, v8
	s_ashr_i32 s29, s28, 31
	v_ashrrev_i32_e32 v19, 31, v18
	v_lshl_add_u64 v[6:7], s[28:29], 1, v[4:5]
	v_lshlrev_b64 v[18:19], 12, v[18:19]
	v_lshl_add_u64 v[18:19], v[6:7], 0, v[18:19]
	global_store_dwordx4 v[18:19], v[14:17], off
	ds_read2_b32 v[14:15], v9 offset0:8 offset1:41
	s_waitcnt lgkmcnt(0)
	v_cvt_pk_bf16_f32 v14, v14, v15
	ds_read2_b32 v[16:17], v9 offset0:74 offset1:107
	s_waitcnt lgkmcnt(0)
	v_cvt_pk_bf16_f32 v15, v16, v17
	ds_read2_b32 v[16:17], v9 offset0:140 offset1:173
	s_waitcnt lgkmcnt(0)
	v_cvt_pk_bf16_f32 v16, v16, v17
	ds_read2_b32 v[18:19], v9 offset0:206 offset1:239
	s_waitcnt lgkmcnt(0)
	v_cvt_pk_bf16_f32 v17, v18, v19
	v_or_b32_e32 v18, s11, v10
	v_ashrrev_i32_e32 v19, 31, v18
	v_lshlrev_b64 v[18:19], 12, v[18:19]
	v_lshl_add_u64 v[18:19], v[6:7], 0, v[18:19]
	global_store_dwordx4 v[18:19], v[14:17], off
	ds_read2_b32 v[14:15], v9 offset0:16 offset1:49
	s_waitcnt lgkmcnt(0)
	v_cvt_pk_bf16_f32 v14, v14, v15
	ds_read2_b32 v[16:17], v9 offset0:82 offset1:115
	s_waitcnt lgkmcnt(0)
	v_cvt_pk_bf16_f32 v15, v16, v17
	ds_read2_b32 v[16:17], v9 offset0:148 offset1:181
	s_waitcnt lgkmcnt(0)
	v_cvt_pk_bf16_f32 v16, v16, v17
	ds_read2_b32 v[18:19], v9 offset0:214 offset1:247
	s_waitcnt lgkmcnt(0)
	v_cvt_pk_bf16_f32 v17, v18, v19
	v_or_b32_e32 v18, s11, v11
	v_ashrrev_i32_e32 v19, 31, v18
	v_lshlrev_b64 v[18:19], 12, v[18:19]
	v_lshl_add_u64 v[18:19], v[6:7], 0, v[18:19]
	global_store_dwordx4 v[18:19], v[14:17], off
	ds_read2_b32 v[14:15], v9 offset0:24 offset1:57
	s_waitcnt lgkmcnt(0)
	v_cvt_pk_bf16_f32 v14, v14, v15
	ds_read2_b32 v[16:17], v9 offset0:90 offset1:123
	s_waitcnt lgkmcnt(0)
	v_cvt_pk_bf16_f32 v15, v16, v17
	ds_read2_b32 v[16:17], v9 offset0:156 offset1:189
	s_waitcnt lgkmcnt(0)
	v_cvt_pk_bf16_f32 v16, v16, v17
	ds_read2_b32 v[18:19], v9 offset0:222 offset1:255
	s_waitcnt lgkmcnt(0)
	v_cvt_pk_bf16_f32 v17, v18, v19
	v_or_b32_e32 v18, s11, v12
	v_ashrrev_i32_e32 v19, 31, v18
	v_lshlrev_b64 v[18:19], 12, v[18:19]
	v_lshl_add_u64 v[6:7], v[6:7], 0, v[18:19]
	global_store_dwordx4 v[6:7], v[14:17], off
	s_waitcnt lgkmcnt(0)
	s_add_i32 s11, s10, 0x680
	s_cmpk_lt_i32 s10, 0x1980
	s_mov_b32 s10, s11
	s_cbranch_scc1 .LBB0_1799
